# as v80 + the no-op s_setprio 0/1 pair in the middle of each 32-MFMA segment removed
# baseline (speedup 1.0000x reference)
.LBB0_119:
	ds_read_b128 v[150:153], v147
	ds_read_b128 v[154:157], v147 offset:1024
	ds_read_b128 v[158:161], v147 offset:2048
	ds_read_b128 v[162:165], v147 offset:3072
	ds_read_b128 v[166:169], v148
	ds_read_b128 v[170:173], v148 offset:1024
	ds_read_b128 v[174:177], v148 offset:2048
	ds_read_b128 v[178:181], v148 offset:3072
	s_add_u32 s20, s54, 0xfffc0080
	s_addc_u32 s21, s55, -1
	s_cmp_eq_u32 s89, 12
	s_cselect_b32 s59, s19, s21
	s_cselect_b32 s58, s85, s20
	s_cselect_b32 s57, s17, s88
	s_cselect_b32 s56, s86, s87
	v_lshl_add_u64 v[214:215], s[54:55], 0, v[136:137]
	s_add_i32 m0, s51, 0xc000
	ds_read_b128 v[182:185], v149
	ds_read_b128 v[186:189], v149 offset:1024
	ds_read_b128 v[190:193], v149 offset:2048
	ds_read_b128 v[194:197], v149 offset:3072
	ds_read_b128 v[198:201], v149 offset:4096
	ds_read_b128 v[202:205], v149 offset:5120
	ds_read_b128 v[206:209], v149 offset:6144
	ds_read_b128 v[210:213], v149 offset:7168
	global_load_lds_dwordx4 v[214:215], off
	v_lshl_add_u64 v[214:215], s[54:55], 0, v[138:139]
	s_add_i32 m0, s51, 0xe000
	s_nop 0
	global_load_lds_dwordx4 v[214:215], off
	s_waitcnt vmcnt(8)
	s_waitcnt lgkmcnt(0)
	s_barrier
	s_setprio 1
	s_waitcnt lgkmcnt(0)
	v_mfma_f32_16x16x32_bf16 v[124:127], v[150:153], v[182:185], v[124:127]
	v_mfma_f32_16x16x32_bf16 v[124:127], v[154:157], v[186:189], v[124:127]
	v_mfma_f32_16x16x32_bf16 v[108:111], v[150:153], v[190:193], v[108:111]
	v_mfma_f32_16x16x32_bf16 v[108:111], v[154:157], v[194:197], v[108:111]
	v_mfma_f32_16x16x32_bf16 v[92:95], v[150:153], v[198:201], v[92:95]
	v_mfma_f32_16x16x32_bf16 v[92:95], v[154:157], v[202:205], v[92:95]
	v_mfma_f32_16x16x32_bf16 v[76:79], v[150:153], v[206:209], v[76:79]
	v_mfma_f32_16x16x32_bf16 v[76:79], v[154:157], v[210:213], v[76:79]
	v_mfma_f32_16x16x32_bf16 v[68:71], v[158:161], v[206:209], v[68:71]
	v_mfma_f32_16x16x32_bf16 v[68:71], v[162:165], v[210:213], v[68:71]
	v_mfma_f32_16x16x32_bf16 v[84:87], v[158:161], v[198:201], v[84:87]
	v_mfma_f32_16x16x32_bf16 v[84:87], v[162:165], v[202:205], v[84:87]
	v_mfma_f32_16x16x32_bf16 v[100:103], v[158:161], v[190:193], v[100:103]
	v_mfma_f32_16x16x32_bf16 v[100:103], v[162:165], v[194:197], v[100:103]
	v_mfma_f32_16x16x32_bf16 v[116:119], v[158:161], v[182:185], v[116:119]
	v_mfma_f32_16x16x32_bf16 v[116:119], v[162:165], v[186:189], v[116:119]
	v_mfma_f32_16x16x32_bf16 v[120:123], v[166:169], v[182:185], v[120:123]
	v_mfma_f32_16x16x32_bf16 v[120:123], v[170:173], v[186:189], v[120:123]
	v_mfma_f32_16x16x32_bf16 v[104:107], v[166:169], v[190:193], v[104:107]
	v_mfma_f32_16x16x32_bf16 v[104:107], v[170:173], v[194:197], v[104:107]
	v_mfma_f32_16x16x32_bf16 v[88:91], v[166:169], v[198:201], v[88:91]
	v_mfma_f32_16x16x32_bf16 v[88:91], v[170:173], v[202:205], v[88:91]
	v_mfma_f32_16x16x32_bf16 v[72:75], v[166:169], v[206:209], v[72:75]
	v_mfma_f32_16x16x32_bf16 v[72:75], v[170:173], v[210:213], v[72:75]
	v_mfma_f32_16x16x32_bf16 v[64:67], v[174:177], v[206:209], v[64:67]
	v_mfma_f32_16x16x32_bf16 v[64:67], v[178:181], v[210:213], v[64:67]
	v_mfma_f32_16x16x32_bf16 v[80:83], v[174:177], v[198:201], v[80:83]
	v_mfma_f32_16x16x32_bf16 v[80:83], v[178:181], v[202:205], v[80:83]
	v_mfma_f32_16x16x32_bf16 v[96:99], v[174:177], v[190:193], v[96:99]
	v_mfma_f32_16x16x32_bf16 v[96:99], v[178:181], v[194:197], v[96:99]
	v_mfma_f32_16x16x32_bf16 v[112:115], v[174:177], v[182:185], v[112:115]
	v_mfma_f32_16x16x32_bf16 v[112:115], v[178:181], v[186:189], v[112:115]
	s_setprio 0
	s_barrier
	s_add_i32 s20, s81, s60
	v_lshl_add_u64 v[214:215], s[56:57], 0, v[132:133]
	s_mov_b32 m0, s20
	ds_read_b128 v[182:185], v149 offset:16384
	ds_read_b128 v[186:189], v149 offset:17408
	ds_read_b128 v[190:193], v149 offset:18432
	ds_read_b128 v[194:197], v149 offset:19456
	ds_read_b128 v[198:201], v149 offset:20480
	ds_read_b128 v[202:205], v149 offset:21504
	ds_read_b128 v[206:209], v149 offset:22528
	ds_read_b128 v[210:213], v149 offset:23552
	global_load_lds_dwordx4 v[214:215], off
	s_add_i32 m0, s20, 0x2000
	s_add_u32 s20, s56, 0x40000
	v_lshl_add_u64 v[216:217], s[56:57], 0, v[128:129]
	s_addc_u32 s21, s57, 0
	s_add_i32 s33, s82, s60
	global_load_lds_dwordx4 v[216:217], off
	v_lshl_add_u64 v[218:219], s[20:21], 0, v[132:133]
	s_mov_b32 m0, s33
	v_lshl_add_u64 v[220:221], s[58:59], 0, v[130:131]
	global_load_lds_dwordx4 v[218:219], off
	v_lshl_add_u64 v[218:219], s[20:21], 0, v[128:129]
	s_add_i32 m0, s33, 0x2000
	s_nop 0
	global_load_lds_dwordx4 v[218:219], off
	v_lshl_add_u64 v[218:219], s[58:59], 0, v[134:135]
	s_mov_b32 m0, s51
	s_nop 0
	global_load_lds_dwordx4 v[218:219], off
	s_mov_b32 m0, s63
	s_nop 0
	global_load_lds_dwordx4 v[220:221], off
	s_waitcnt vmcnt(8)
	s_waitcnt lgkmcnt(0)
	s_barrier
	s_setprio 1
	s_waitcnt lgkmcnt(0)
	v_mfma_f32_16x16x32_bf16 v[60:63], v[150:153], v[182:185], v[60:63]
	v_mfma_f32_16x16x32_bf16 v[60:63], v[154:157], v[186:189], v[60:63]
	v_mfma_f32_16x16x32_bf16 v[44:47], v[150:153], v[190:193], v[44:47]
	v_mfma_f32_16x16x32_bf16 v[44:47], v[154:157], v[194:197], v[44:47]
	v_mfma_f32_16x16x32_bf16 v[28:31], v[150:153], v[198:201], v[28:31]
	v_mfma_f32_16x16x32_bf16 v[28:31], v[154:157], v[202:205], v[28:31]
	v_mfma_f32_16x16x32_bf16 v[12:15], v[150:153], v[206:209], v[12:15]
	v_mfma_f32_16x16x32_bf16 v[12:15], v[154:157], v[210:213], v[12:15]
	v_mfma_f32_16x16x32_bf16 v[4:7], v[158:161], v[206:209], v[4:7]
	v_mfma_f32_16x16x32_bf16 v[4:7], v[162:165], v[210:213], v[4:7]
	v_mfma_f32_16x16x32_bf16 v[20:23], v[158:161], v[198:201], v[20:23]
	v_mfma_f32_16x16x32_bf16 v[20:23], v[162:165], v[202:205], v[20:23]
	v_mfma_f32_16x16x32_bf16 v[36:39], v[158:161], v[190:193], v[36:39]
	v_mfma_f32_16x16x32_bf16 v[36:39], v[162:165], v[194:197], v[36:39]
	v_mfma_f32_16x16x32_bf16 v[52:55], v[158:161], v[182:185], v[52:55]
	v_mfma_f32_16x16x32_bf16 v[52:55], v[162:165], v[186:189], v[52:55]
	v_mfma_f32_16x16x32_bf16 v[56:59], v[166:169], v[182:185], v[56:59]
	v_mfma_f32_16x16x32_bf16 v[56:59], v[170:173], v[186:189], v[56:59]
	v_mfma_f32_16x16x32_bf16 v[40:43], v[166:169], v[190:193], v[40:43]
	v_mfma_f32_16x16x32_bf16 v[40:43], v[170:173], v[194:197], v[40:43]
	v_mfma_f32_16x16x32_bf16 v[24:27], v[166:169], v[198:201], v[24:27]
	v_mfma_f32_16x16x32_bf16 v[24:27], v[170:173], v[202:205], v[24:27]
	v_mfma_f32_16x16x32_bf16 v[8:11], v[166:169], v[206:209], v[8:11]
	v_mfma_f32_16x16x32_bf16 v[8:11], v[170:173], v[210:213], v[8:11]
	v_mfma_f32_16x16x32_bf16 v[0:3], v[174:177], v[206:209], v[0:3]
	v_mfma_f32_16x16x32_bf16 v[0:3], v[178:181], v[210:213], v[0:3]
	v_mfma_f32_16x16x32_bf16 v[16:19], v[174:177], v[198:201], v[16:19]
	v_mfma_f32_16x16x32_bf16 v[16:19], v[178:181], v[202:205], v[16:19]
	v_mfma_f32_16x16x32_bf16 v[32:35], v[174:177], v[190:193], v[32:35]
	v_mfma_f32_16x16x32_bf16 v[32:35], v[178:181], v[194:197], v[32:35]
	v_mfma_f32_16x16x32_bf16 v[48:51], v[174:177], v[182:185], v[48:51]
	v_mfma_f32_16x16x32_bf16 v[48:51], v[178:181], v[186:189], v[48:51]
	s_setprio 0
	s_barrier
	s_add_i32 s33, 0, 0x18000
	s_add_i32 s75, 0, 0x1c000
	v_add_u32_e32 v162, s33, v145
	v_add_u32_e32 v178, s75, v145
	ds_read_b128 v[150:153], v162
	ds_read_b128 v[154:157], v162 offset:1024
	ds_read_b128 v[158:161], v162 offset:2048
	ds_read_b128 v[162:165], v162 offset:3072
	ds_read_b128 v[166:169], v178
	ds_read_b128 v[170:173], v178 offset:1024
	ds_read_b128 v[174:177], v178 offset:2048
	ds_read_b128 v[178:181], v178 offset:3072
	s_add_u32 s20, s58, 0x40000
	s_addc_u32 s21, s59, 0
	s_mov_b32 m0, s64
	v_lshl_add_u64 v[222:223], s[20:21], 0, v[134:135]
	ds_read_b128 v[182:185], v149 offset:32768
	ds_read_b128 v[186:189], v149 offset:33792
	ds_read_b128 v[190:193], v149 offset:34816
	ds_read_b128 v[194:197], v149 offset:35840
	ds_read_b128 v[198:201], v149 offset:36864
	ds_read_b128 v[202:205], v149 offset:37888
	ds_read_b128 v[206:209], v149 offset:38912
	ds_read_b128 v[210:213], v149 offset:39936
	global_load_lds_dwordx4 v[222:223], off
	v_lshl_add_u64 v[222:223], s[20:21], 0, v[130:131]
	s_mov_b32 m0, s65
	s_nop 0
	global_load_lds_dwordx4 v[222:223], off
	s_waitcnt vmcnt(8)
	s_waitcnt lgkmcnt(0)
	s_barrier
	s_setprio 1
	s_waitcnt lgkmcnt(0)
	v_mfma_f32_16x16x32_bf16 v[124:127], v[150:153], v[182:185], v[124:127]
	v_mfma_f32_16x16x32_bf16 v[124:127], v[154:157], v[186:189], v[124:127]
	v_mfma_f32_16x16x32_bf16 v[108:111], v[150:153], v[190:193], v[108:111]
	v_mfma_f32_16x16x32_bf16 v[108:111], v[154:157], v[194:197], v[108:111]
	v_mfma_f32_16x16x32_bf16 v[92:95], v[150:153], v[198:201], v[92:95]
	v_mfma_f32_16x16x32_bf16 v[92:95], v[154:157], v[202:205], v[92:95]
	v_mfma_f32_16x16x32_bf16 v[76:79], v[150:153], v[206:209], v[76:79]
	v_mfma_f32_16x16x32_bf16 v[76:79], v[154:157], v[210:213], v[76:79]
	v_mfma_f32_16x16x32_bf16 v[68:71], v[158:161], v[206:209], v[68:71]
	v_mfma_f32_16x16x32_bf16 v[68:71], v[162:165], v[210:213], v[68:71]
	v_mfma_f32_16x16x32_bf16 v[84:87], v[158:161], v[198:201], v[84:87]
	v_mfma_f32_16x16x32_bf16 v[84:87], v[162:165], v[202:205], v[84:87]
	v_mfma_f32_16x16x32_bf16 v[100:103], v[158:161], v[190:193], v[100:103]
	v_mfma_f32_16x16x32_bf16 v[100:103], v[162:165], v[194:197], v[100:103]
	v_mfma_f32_16x16x32_bf16 v[116:119], v[158:161], v[182:185], v[116:119]
	v_mfma_f32_16x16x32_bf16 v[116:119], v[162:165], v[186:189], v[116:119]
	v_mfma_f32_16x16x32_bf16 v[120:123], v[166:169], v[182:185], v[120:123]
	v_mfma_f32_16x16x32_bf16 v[120:123], v[170:173], v[186:189], v[120:123]
	v_mfma_f32_16x16x32_bf16 v[104:107], v[166:169], v[190:193], v[104:107]
	v_mfma_f32_16x16x32_bf16 v[104:107], v[170:173], v[194:197], v[104:107]
	v_mfma_f32_16x16x32_bf16 v[88:91], v[166:169], v[198:201], v[88:91]
	v_mfma_f32_16x16x32_bf16 v[88:91], v[170:173], v[202:205], v[88:91]
	v_mfma_f32_16x16x32_bf16 v[72:75], v[166:169], v[206:209], v[72:75]
	v_mfma_f32_16x16x32_bf16 v[72:75], v[170:173], v[210:213], v[72:75]
	v_mfma_f32_16x16x32_bf16 v[64:67], v[174:177], v[206:209], v[64:67]
	v_mfma_f32_16x16x32_bf16 v[64:67], v[178:181], v[210:213], v[64:67]
	v_mfma_f32_16x16x32_bf16 v[80:83], v[174:177], v[198:201], v[80:83]
	v_mfma_f32_16x16x32_bf16 v[80:83], v[178:181], v[202:205], v[80:83]
	v_mfma_f32_16x16x32_bf16 v[96:99], v[174:177], v[190:193], v[96:99]
	v_mfma_f32_16x16x32_bf16 v[96:99], v[178:181], v[194:197], v[96:99]
	v_mfma_f32_16x16x32_bf16 v[112:115], v[174:177], v[182:185], v[112:115]
	v_mfma_f32_16x16x32_bf16 v[112:115], v[178:181], v[186:189], v[112:115]
	s_setprio 0
	s_barrier
	s_add_i32 s20, s33, s60
	v_lshl_add_u64 v[214:215], v[214:215], 0, s[6:7]
	s_mov_b32 m0, s20
	ds_read_b128 v[182:185], v149 offset:49152
	ds_read_b128 v[186:189], v149 offset:50176
	ds_read_b128 v[190:193], v149 offset:51200
	ds_read_b128 v[194:197], v149 offset:52224
	ds_read_b128 v[198:201], v149 offset:53248
	ds_read_b128 v[202:205], v149 offset:54272
	ds_read_b128 v[206:209], v149 offset:55296
	ds_read_b128 v[210:213], v149 offset:56320
	global_load_lds_dwordx4 v[214:215], off
	s_add_i32 m0, s20, 0x2000
	s_add_u32 s20, s56, 0x40080
	v_lshl_add_u64 v[214:215], v[216:217], 0, s[6:7]
	s_addc_u32 s21, s57, 0
	s_add_i32 s33, s75, s60
	global_load_lds_dwordx4 v[214:215], off
	v_lshl_add_u64 v[214:215], s[20:21], 0, v[132:133]
	s_mov_b32 m0, s33
	s_nop 0
	global_load_lds_dwordx4 v[214:215], off
	v_lshl_add_u64 v[214:215], s[20:21], 0, v[128:129]
	s_add_i32 m0, s33, 0x2000
	s_nop 0
	global_load_lds_dwordx4 v[214:215], off
	v_lshl_add_u64 v[214:215], v[218:219], 0, s[6:7]
	s_mov_b32 m0, s77
	s_nop 0
	global_load_lds_dwordx4 v[214:215], off
	v_lshl_add_u64 v[214:215], v[220:221], 0, s[6:7]
	s_mov_b32 m0, s78
	s_nop 0
	global_load_lds_dwordx4 v[214:215], off
	s_waitcnt vmcnt(8)
	s_waitcnt lgkmcnt(0)
	s_barrier
	s_setprio 1
	s_waitcnt lgkmcnt(0)
	v_mfma_f32_16x16x32_bf16 v[60:63], v[150:153], v[182:185], v[60:63]
	v_mfma_f32_16x16x32_bf16 v[60:63], v[154:157], v[186:189], v[60:63]
	v_mfma_f32_16x16x32_bf16 v[44:47], v[150:153], v[190:193], v[44:47]
	v_mfma_f32_16x16x32_bf16 v[44:47], v[154:157], v[194:197], v[44:47]
	v_mfma_f32_16x16x32_bf16 v[28:31], v[150:153], v[198:201], v[28:31]
	v_mfma_f32_16x16x32_bf16 v[28:31], v[154:157], v[202:205], v[28:31]
	v_mfma_f32_16x16x32_bf16 v[12:15], v[150:153], v[206:209], v[12:15]
	v_mfma_f32_16x16x32_bf16 v[12:15], v[154:157], v[210:213], v[12:15]
	v_mfma_f32_16x16x32_bf16 v[4:7], v[158:161], v[206:209], v[4:7]
	v_mfma_f32_16x16x32_bf16 v[4:7], v[162:165], v[210:213], v[4:7]
	v_mfma_f32_16x16x32_bf16 v[20:23], v[158:161], v[198:201], v[20:23]
	v_mfma_f32_16x16x32_bf16 v[20:23], v[162:165], v[202:205], v[20:23]
	v_mfma_f32_16x16x32_bf16 v[36:39], v[158:161], v[190:193], v[36:39]
	v_mfma_f32_16x16x32_bf16 v[36:39], v[162:165], v[194:197], v[36:39]
	v_mfma_f32_16x16x32_bf16 v[52:55], v[158:161], v[182:185], v[52:55]
	v_mfma_f32_16x16x32_bf16 v[52:55], v[162:165], v[186:189], v[52:55]
	v_mfma_f32_16x16x32_bf16 v[56:59], v[166:169], v[182:185], v[56:59]
	v_mfma_f32_16x16x32_bf16 v[56:59], v[170:173], v[186:189], v[56:59]
	v_mfma_f32_16x16x32_bf16 v[40:43], v[166:169], v[190:193], v[40:43]
	v_mfma_f32_16x16x32_bf16 v[40:43], v[170:173], v[194:197], v[40:43]
	v_mfma_f32_16x16x32_bf16 v[24:27], v[166:169], v[198:201], v[24:27]
	v_mfma_f32_16x16x32_bf16 v[24:27], v[170:173], v[202:205], v[24:27]
	v_mfma_f32_16x16x32_bf16 v[8:11], v[166:169], v[206:209], v[8:11]
	v_mfma_f32_16x16x32_bf16 v[8:11], v[170:173], v[210:213], v[8:11]
	v_mfma_f32_16x16x32_bf16 v[0:3], v[174:177], v[206:209], v[0:3]
	v_mfma_f32_16x16x32_bf16 v[0:3], v[178:181], v[210:213], v[0:3]
	v_mfma_f32_16x16x32_bf16 v[16:19], v[174:177], v[198:201], v[16:19]
	v_mfma_f32_16x16x32_bf16 v[16:19], v[178:181], v[202:205], v[16:19]
	v_mfma_f32_16x16x32_bf16 v[32:35], v[174:177], v[190:193], v[32:35]
	v_mfma_f32_16x16x32_bf16 v[32:35], v[178:181], v[194:197], v[32:35]
	v_mfma_f32_16x16x32_bf16 v[48:51], v[174:177], v[182:185], v[48:51]
	v_mfma_f32_16x16x32_bf16 v[48:51], v[178:181], v[186:189], v[48:51]
	s_setprio 0
	s_barrier
	s_add_i32 s89, s89, 2
	s_add_u32 s54, s54, 0x100
	s_addc_u32 s55, s55, 0
	s_add_u32 s87, s87, 0x100
	s_addc_u32 s88, s88, 0
	s_cmp_gt_u32 s89, 13
	s_cbranch_scc0 .LBB0_119
	s_and_b64 vcc, exec, s[8:9]
	s_cbranch_vccz .LBB0_122
	s_barrier

.LBB0_201:
	ds_read_b128 v[128:131], v207
	ds_read_b128 v[132:135], v207 offset:1024
	ds_read_b128 v[136:139], v207 offset:2048
	ds_read_b128 v[140:143], v207 offset:3072
	ds_read_b128 v[144:147], v208
	ds_read_b128 v[148:151], v208 offset:1024
	ds_read_b128 v[152:155], v208 offset:2048
	ds_read_b128 v[156:159], v208 offset:3072
	s_add_u32 s56, s54, 0x100
	s_addc_u32 s57, s55, 0
	s_cmp_eq_u32 s91, 40
	s_cselect_b32 s61, s1, s57
	s_cselect_b32 s60, s0, s56
	s_cselect_b32 s59, s51, s90
	s_cselect_b32 s58, s50, s89
	v_lshl_add_u64 v[216:217], s[54:55], 0, v[184:185]
	s_add_i32 m0, s63, 0xc000
	ds_read_b128 v[160:163], v209
	ds_read_b128 v[164:167], v209 offset:1024
	ds_read_b128 v[168:171], v209 offset:2048
	ds_read_b128 v[172:175], v209 offset:3072
	ds_read_b128 v[192:195], v209 offset:4096
	ds_read_b128 v[196:199], v209 offset:5120
	ds_read_b128 v[200:203], v209 offset:6144
	ds_read_b128 v[212:215], v209 offset:7168
	global_load_lds_dwordx4 v[216:217], off
	v_lshl_add_u64 v[216:217], s[54:55], 0, v[186:187]
	s_add_i32 m0, s63, 0xe000
	s_nop 0
	global_load_lds_dwordx4 v[216:217], off
	s_waitcnt vmcnt(8)
	s_waitcnt lgkmcnt(0)
	s_barrier
	s_setprio 1
	s_waitcnt lgkmcnt(0)
	v_mfma_f32_16x16x32_bf16 v[124:127], v[128:131], v[160:163], v[124:127]
	v_mfma_f32_16x16x32_bf16 v[124:127], v[132:135], v[164:167], v[124:127]
	v_mfma_f32_16x16x32_bf16 v[108:111], v[128:131], v[168:171], v[108:111]
	v_mfma_f32_16x16x32_bf16 v[108:111], v[132:135], v[172:175], v[108:111]
	v_mfma_f32_16x16x32_bf16 v[92:95], v[128:131], v[192:195], v[92:95]
	v_mfma_f32_16x16x32_bf16 v[92:95], v[132:135], v[196:199], v[92:95]
	v_mfma_f32_16x16x32_bf16 v[76:79], v[128:131], v[200:203], v[76:79]
	v_mfma_f32_16x16x32_bf16 v[76:79], v[132:135], v[212:215], v[76:79]
	v_mfma_f32_16x16x32_bf16 v[72:75], v[136:139], v[200:203], v[72:75]
	v_mfma_f32_16x16x32_bf16 v[72:75], v[140:143], v[212:215], v[72:75]
	v_mfma_f32_16x16x32_bf16 v[88:91], v[136:139], v[192:195], v[88:91]
	v_mfma_f32_16x16x32_bf16 v[88:91], v[140:143], v[196:199], v[88:91]
	v_mfma_f32_16x16x32_bf16 v[104:107], v[136:139], v[168:171], v[104:107]
	v_mfma_f32_16x16x32_bf16 v[104:107], v[140:143], v[172:175], v[104:107]
	v_mfma_f32_16x16x32_bf16 v[120:123], v[136:139], v[160:163], v[120:123]
	v_mfma_f32_16x16x32_bf16 v[120:123], v[140:143], v[164:167], v[120:123]
	v_mfma_f32_16x16x32_bf16 v[116:119], v[144:147], v[160:163], v[116:119]
	v_mfma_f32_16x16x32_bf16 v[116:119], v[148:151], v[164:167], v[116:119]
	v_mfma_f32_16x16x32_bf16 v[100:103], v[144:147], v[168:171], v[100:103]
	v_mfma_f32_16x16x32_bf16 v[100:103], v[148:151], v[172:175], v[100:103]
	v_mfma_f32_16x16x32_bf16 v[84:87], v[144:147], v[192:195], v[84:87]
	v_mfma_f32_16x16x32_bf16 v[84:87], v[148:151], v[196:199], v[84:87]
	v_mfma_f32_16x16x32_bf16 v[68:71], v[144:147], v[200:203], v[68:71]
	v_mfma_f32_16x16x32_bf16 v[68:71], v[148:151], v[212:215], v[68:71]
	v_mfma_f32_16x16x32_bf16 v[64:67], v[152:155], v[200:203], v[64:67]
	v_mfma_f32_16x16x32_bf16 v[64:67], v[156:159], v[212:215], v[64:67]
	v_mfma_f32_16x16x32_bf16 v[80:83], v[152:155], v[192:195], v[80:83]
	v_mfma_f32_16x16x32_bf16 v[80:83], v[156:159], v[196:199], v[80:83]
	v_mfma_f32_16x16x32_bf16 v[96:99], v[152:155], v[168:171], v[96:99]
	v_mfma_f32_16x16x32_bf16 v[96:99], v[156:159], v[172:175], v[96:99]
	v_mfma_f32_16x16x32_bf16 v[112:115], v[152:155], v[160:163], v[112:115]
	v_mfma_f32_16x16x32_bf16 v[112:115], v[156:159], v[164:167], v[112:115]
	s_setprio 0
	s_barrier
	s_add_i32 s20, s83, s62
	v_lshl_add_u64 v[216:217], s[58:59], 0, v[178:179]
	s_mov_b32 m0, s20
	ds_read_b128 v[160:163], v209 offset:16384
	ds_read_b128 v[164:167], v209 offset:17408
	ds_read_b128 v[168:171], v209 offset:18432
	ds_read_b128 v[172:175], v209 offset:19456
	ds_read_b128 v[192:195], v209 offset:20480
	ds_read_b128 v[196:199], v209 offset:21504
	ds_read_b128 v[200:203], v209 offset:22528
	ds_read_b128 v[212:215], v209 offset:23552
	global_load_lds_dwordx4 v[216:217], off
	s_add_i32 m0, s20, 0x2000
	s_add_u32 s20, s58, 0xb0000
	v_lshl_add_u64 v[218:219], s[58:59], 0, v[182:183]
	s_addc_u32 s21, s59, 0
	s_add_i32 s33, s84, s62
	global_load_lds_dwordx4 v[218:219], off
	v_lshl_add_u64 v[220:221], s[20:21], 0, v[178:179]
	s_mov_b32 m0, s33
	v_lshl_add_u64 v[222:223], s[60:61], 0, v[180:181]
	global_load_lds_dwordx4 v[220:221], off
	v_lshl_add_u64 v[220:221], s[20:21], 0, v[182:183]
	s_add_i32 m0, s33, 0x2000
	s_nop 0
	global_load_lds_dwordx4 v[220:221], off
	v_lshl_add_u64 v[220:221], s[60:61], 0, v[176:177]
	s_mov_b32 m0, s63
	s_nop 0
	global_load_lds_dwordx4 v[220:221], off
	s_mov_b32 m0, s64
	s_nop 0
	global_load_lds_dwordx4 v[222:223], off
	s_waitcnt vmcnt(8)
	s_waitcnt lgkmcnt(0)
	s_barrier
	s_setprio 1
	s_waitcnt lgkmcnt(0)
	v_mfma_f32_16x16x32_bf16 v[60:63], v[128:131], v[160:163], v[60:63]
	v_mfma_f32_16x16x32_bf16 v[60:63], v[132:135], v[164:167], v[60:63]
	v_mfma_f32_16x16x32_bf16 v[44:47], v[128:131], v[168:171], v[44:47]
	v_mfma_f32_16x16x32_bf16 v[44:47], v[132:135], v[172:175], v[44:47]
	v_mfma_f32_16x16x32_bf16 v[28:31], v[128:131], v[192:195], v[28:31]
	v_mfma_f32_16x16x32_bf16 v[28:31], v[132:135], v[196:199], v[28:31]
	v_mfma_f32_16x16x32_bf16 v[12:15], v[128:131], v[200:203], v[12:15]
	v_mfma_f32_16x16x32_bf16 v[12:15], v[132:135], v[212:215], v[12:15]
	v_mfma_f32_16x16x32_bf16 v[8:11], v[136:139], v[200:203], v[8:11]
	v_mfma_f32_16x16x32_bf16 v[8:11], v[140:143], v[212:215], v[8:11]
	v_mfma_f32_16x16x32_bf16 v[24:27], v[136:139], v[192:195], v[24:27]
	v_mfma_f32_16x16x32_bf16 v[24:27], v[140:143], v[196:199], v[24:27]
	v_mfma_f32_16x16x32_bf16 v[40:43], v[136:139], v[168:171], v[40:43]
	v_mfma_f32_16x16x32_bf16 v[40:43], v[140:143], v[172:175], v[40:43]
	v_mfma_f32_16x16x32_bf16 v[56:59], v[136:139], v[160:163], v[56:59]
	v_mfma_f32_16x16x32_bf16 v[56:59], v[140:143], v[164:167], v[56:59]
	v_mfma_f32_16x16x32_bf16 v[52:55], v[144:147], v[160:163], v[52:55]
	v_mfma_f32_16x16x32_bf16 v[52:55], v[148:151], v[164:167], v[52:55]
	v_mfma_f32_16x16x32_bf16 v[36:39], v[144:147], v[168:171], v[36:39]
	v_mfma_f32_16x16x32_bf16 v[36:39], v[148:151], v[172:175], v[36:39]
	v_mfma_f32_16x16x32_bf16 v[20:23], v[144:147], v[192:195], v[20:23]
	v_mfma_f32_16x16x32_bf16 v[20:23], v[148:151], v[196:199], v[20:23]
	v_mfma_f32_16x16x32_bf16 v[4:7], v[144:147], v[200:203], v[4:7]
	v_mfma_f32_16x16x32_bf16 v[4:7], v[148:151], v[212:215], v[4:7]
	v_mfma_f32_16x16x32_bf16 v[0:3], v[152:155], v[200:203], v[0:3]
	v_mfma_f32_16x16x32_bf16 v[0:3], v[156:159], v[212:215], v[0:3]
	v_mfma_f32_16x16x32_bf16 v[16:19], v[152:155], v[192:195], v[16:19]
	v_mfma_f32_16x16x32_bf16 v[16:19], v[156:159], v[196:199], v[16:19]
	v_mfma_f32_16x16x32_bf16 v[32:35], v[152:155], v[168:171], v[32:35]
	v_mfma_f32_16x16x32_bf16 v[32:35], v[156:159], v[172:175], v[32:35]
	v_mfma_f32_16x16x32_bf16 v[48:51], v[152:155], v[160:163], v[48:51]
	v_mfma_f32_16x16x32_bf16 v[48:51], v[156:159], v[164:167], v[48:51]
	s_setprio 0
	s_barrier
	s_add_i32 s33, 0, 0x18000
	s_add_i32 s54, 0, 0x1c000
	v_add_u32_e32 v140, s33, v205
	v_add_u32_e32 v156, s54, v205
	ds_read_b128 v[128:131], v140
	ds_read_b128 v[132:135], v140 offset:1024
	ds_read_b128 v[136:139], v140 offset:2048
	ds_read_b128 v[140:143], v140 offset:3072
	ds_read_b128 v[144:147], v156
	ds_read_b128 v[148:151], v156 offset:1024
	ds_read_b128 v[152:155], v156 offset:2048
	ds_read_b128 v[156:159], v156 offset:3072
	s_add_u32 s20, s60, 0xb0000
	s_addc_u32 s21, s61, 0
	s_mov_b32 m0, s65
	v_lshl_add_u64 v[224:225], s[20:21], 0, v[176:177]
	ds_read_b128 v[160:163], v209 offset:32768
	ds_read_b128 v[164:167], v209 offset:33792
	ds_read_b128 v[168:171], v209 offset:34816
	ds_read_b128 v[172:175], v209 offset:35840
	ds_read_b128 v[192:195], v209 offset:36864
	ds_read_b128 v[196:199], v209 offset:37888
	ds_read_b128 v[200:203], v209 offset:38912
	ds_read_b128 v[212:215], v209 offset:39936
	global_load_lds_dwordx4 v[224:225], off
	v_lshl_add_u64 v[224:225], s[20:21], 0, v[180:181]
	s_mov_b32 m0, s76
	s_nop 0
	global_load_lds_dwordx4 v[224:225], off
	s_waitcnt vmcnt(8)
	s_waitcnt lgkmcnt(0)
	s_barrier
	s_setprio 1
	s_waitcnt lgkmcnt(0)
	v_mfma_f32_16x16x32_bf16 v[124:127], v[128:131], v[160:163], v[124:127]
	v_mfma_f32_16x16x32_bf16 v[124:127], v[132:135], v[164:167], v[124:127]
	v_mfma_f32_16x16x32_bf16 v[108:111], v[128:131], v[168:171], v[108:111]
	v_mfma_f32_16x16x32_bf16 v[108:111], v[132:135], v[172:175], v[108:111]
	v_mfma_f32_16x16x32_bf16 v[92:95], v[128:131], v[192:195], v[92:95]
	v_mfma_f32_16x16x32_bf16 v[92:95], v[132:135], v[196:199], v[92:95]
	v_mfma_f32_16x16x32_bf16 v[76:79], v[128:131], v[200:203], v[76:79]
	v_mfma_f32_16x16x32_bf16 v[76:79], v[132:135], v[212:215], v[76:79]
	v_mfma_f32_16x16x32_bf16 v[72:75], v[136:139], v[200:203], v[72:75]
	v_mfma_f32_16x16x32_bf16 v[72:75], v[140:143], v[212:215], v[72:75]
	v_mfma_f32_16x16x32_bf16 v[88:91], v[136:139], v[192:195], v[88:91]
	v_mfma_f32_16x16x32_bf16 v[88:91], v[140:143], v[196:199], v[88:91]
	v_mfma_f32_16x16x32_bf16 v[104:107], v[136:139], v[168:171], v[104:107]
	v_mfma_f32_16x16x32_bf16 v[104:107], v[140:143], v[172:175], v[104:107]
	v_mfma_f32_16x16x32_bf16 v[120:123], v[136:139], v[160:163], v[120:123]
	v_mfma_f32_16x16x32_bf16 v[120:123], v[140:143], v[164:167], v[120:123]
	v_mfma_f32_16x16x32_bf16 v[116:119], v[144:147], v[160:163], v[116:119]
	v_mfma_f32_16x16x32_bf16 v[116:119], v[148:151], v[164:167], v[116:119]
	v_mfma_f32_16x16x32_bf16 v[100:103], v[144:147], v[168:171], v[100:103]
	v_mfma_f32_16x16x32_bf16 v[100:103], v[148:151], v[172:175], v[100:103]
	v_mfma_f32_16x16x32_bf16 v[84:87], v[144:147], v[192:195], v[84:87]
	v_mfma_f32_16x16x32_bf16 v[84:87], v[148:151], v[196:199], v[84:87]
	v_mfma_f32_16x16x32_bf16 v[68:71], v[144:147], v[200:203], v[68:71]
	v_mfma_f32_16x16x32_bf16 v[68:71], v[148:151], v[212:215], v[68:71]
	v_mfma_f32_16x16x32_bf16 v[64:67], v[152:155], v[200:203], v[64:67]
	v_mfma_f32_16x16x32_bf16 v[64:67], v[156:159], v[212:215], v[64:67]
	v_mfma_f32_16x16x32_bf16 v[80:83], v[152:155], v[192:195], v[80:83]
	v_mfma_f32_16x16x32_bf16 v[80:83], v[156:159], v[196:199], v[80:83]
	v_mfma_f32_16x16x32_bf16 v[96:99], v[152:155], v[168:171], v[96:99]
	v_mfma_f32_16x16x32_bf16 v[96:99], v[156:159], v[172:175], v[96:99]
	v_mfma_f32_16x16x32_bf16 v[112:115], v[152:155], v[160:163], v[112:115]
	v_mfma_f32_16x16x32_bf16 v[112:115], v[156:159], v[164:167], v[112:115]
	s_setprio 0
	s_barrier
	s_add_i32 s20, s33, s62
	v_lshl_add_u64 v[216:217], v[216:217], 0, s[18:19]
	s_mov_b32 m0, s20
	ds_read_b128 v[160:163], v209 offset:49152
	ds_read_b128 v[164:167], v209 offset:50176
	ds_read_b128 v[168:171], v209 offset:51200
	ds_read_b128 v[172:175], v209 offset:52224
	ds_read_b128 v[192:195], v209 offset:53248
	ds_read_b128 v[196:199], v209 offset:54272
	ds_read_b128 v[200:203], v209 offset:55296
	ds_read_b128 v[212:215], v209 offset:56320
	global_load_lds_dwordx4 v[216:217], off
	s_add_i32 m0, s20, 0x2000
	s_add_u32 s20, s58, 0xb0080
	v_lshl_add_u64 v[216:217], v[218:219], 0, s[18:19]
	s_addc_u32 s21, s59, 0
	s_add_i32 s33, s54, s62
	global_load_lds_dwordx4 v[216:217], off
	v_lshl_add_u64 v[216:217], s[20:21], 0, v[178:179]
	s_mov_b32 m0, s33
	s_nop 0
	global_load_lds_dwordx4 v[216:217], off
	v_lshl_add_u64 v[216:217], s[20:21], 0, v[182:183]
	s_add_i32 m0, s33, 0x2000
	s_nop 0
	global_load_lds_dwordx4 v[216:217], off
	v_lshl_add_u64 v[216:217], v[220:221], 0, s[18:19]
	s_mov_b32 m0, s78
	s_nop 0
	global_load_lds_dwordx4 v[216:217], off
	v_lshl_add_u64 v[216:217], v[222:223], 0, s[18:19]
	s_mov_b32 m0, s79
	s_nop 0
	global_load_lds_dwordx4 v[216:217], off
	s_waitcnt vmcnt(8)
	s_waitcnt lgkmcnt(0)
	s_barrier
	s_setprio 1
	s_waitcnt lgkmcnt(0)
	v_mfma_f32_16x16x32_bf16 v[60:63], v[128:131], v[160:163], v[60:63]
	v_mfma_f32_16x16x32_bf16 v[60:63], v[132:135], v[164:167], v[60:63]
	v_mfma_f32_16x16x32_bf16 v[44:47], v[128:131], v[168:171], v[44:47]
	v_mfma_f32_16x16x32_bf16 v[44:47], v[132:135], v[172:175], v[44:47]
	v_mfma_f32_16x16x32_bf16 v[28:31], v[128:131], v[192:195], v[28:31]
	v_mfma_f32_16x16x32_bf16 v[28:31], v[132:135], v[196:199], v[28:31]
	v_mfma_f32_16x16x32_bf16 v[12:15], v[128:131], v[200:203], v[12:15]
	v_mfma_f32_16x16x32_bf16 v[12:15], v[132:135], v[212:215], v[12:15]
	v_mfma_f32_16x16x32_bf16 v[8:11], v[136:139], v[200:203], v[8:11]
	v_mfma_f32_16x16x32_bf16 v[8:11], v[140:143], v[212:215], v[8:11]
	v_mfma_f32_16x16x32_bf16 v[24:27], v[136:139], v[192:195], v[24:27]
	v_mfma_f32_16x16x32_bf16 v[24:27], v[140:143], v[196:199], v[24:27]
	v_mfma_f32_16x16x32_bf16 v[40:43], v[136:139], v[168:171], v[40:43]
	v_mfma_f32_16x16x32_bf16 v[40:43], v[140:143], v[172:175], v[40:43]
	v_mfma_f32_16x16x32_bf16 v[56:59], v[136:139], v[160:163], v[56:59]
	v_mfma_f32_16x16x32_bf16 v[56:59], v[140:143], v[164:167], v[56:59]
	v_mfma_f32_16x16x32_bf16 v[52:55], v[144:147], v[160:163], v[52:55]
	v_mfma_f32_16x16x32_bf16 v[52:55], v[148:151], v[164:167], v[52:55]
	v_mfma_f32_16x16x32_bf16 v[36:39], v[144:147], v[168:171], v[36:39]
	v_mfma_f32_16x16x32_bf16 v[36:39], v[148:151], v[172:175], v[36:39]
	v_mfma_f32_16x16x32_bf16 v[20:23], v[144:147], v[192:195], v[20:23]
	v_mfma_f32_16x16x32_bf16 v[20:23], v[148:151], v[196:199], v[20:23]
	v_mfma_f32_16x16x32_bf16 v[4:7], v[144:147], v[200:203], v[4:7]
	v_mfma_f32_16x16x32_bf16 v[4:7], v[148:151], v[212:215], v[4:7]
	v_mfma_f32_16x16x32_bf16 v[0:3], v[152:155], v[200:203], v[0:3]
	v_mfma_f32_16x16x32_bf16 v[0:3], v[156:159], v[212:215], v[0:3]
	v_mfma_f32_16x16x32_bf16 v[16:19], v[152:155], v[192:195], v[16:19]
	v_mfma_f32_16x16x32_bf16 v[16:19], v[156:159], v[196:199], v[16:19]
	v_mfma_f32_16x16x32_bf16 v[32:35], v[152:155], v[168:171], v[32:35]
	v_mfma_f32_16x16x32_bf16 v[32:35], v[156:159], v[172:175], v[32:35]
	v_mfma_f32_16x16x32_bf16 v[48:51], v[152:155], v[160:163], v[48:51]
	v_mfma_f32_16x16x32_bf16 v[48:51], v[156:159], v[164:167], v[48:51]
	s_setprio 0
	s_barrier
	s_add_i32 s91, s91, 2
	s_add_u32 s89, s89, 0x100
	s_addc_u32 s90, s90, 0
	s_cmp_gt_u32 s91, 41
	s_mov_b64 s[54:55], s[56:57]
	s_cbranch_scc0 .LBB0_201
	s_and_b64 vcc, exec, s[48:49]
	s_cbranch_vccz .LBB0_204
	s_barrier

.LBB0_287:
	ds_read_b128 v[128:131], v177
	ds_read_b128 v[132:135], v177 offset:1024
	ds_read_b128 v[164:167], v177 offset:2048
	ds_read_b128 v[194:197], v177 offset:3072
	ds_read_b128 v[198:201], v181
	ds_read_b128 v[202:205], v181 offset:1024
	ds_read_b128 v[206:209], v181 offset:2048
	ds_read_b128 v[214:217], v181 offset:3072
	s_add_u32 s20, s58, 0xfffc0080
	s_addc_u32 s21, s59, -1
	s_cmp_eq_u32 s97, 12
	s_cselect_b32 s63, s7, s21
	s_cselect_b32 s62, s19, s20
	s_cselect_b32 s61, s17, s96
	s_cselect_b32 s60, s57, s95
	v_lshl_add_u64 v[170:171], s[58:59], 0, v[156:157]
	s_add_i32 m0, s65, 0xc000
	ds_read_b128 v[218:221], v185
	ds_read_b128 v[222:225], v185 offset:1024
	ds_read_b128 v[226:229], v185 offset:2048
	ds_read_b128 v[230:233], v185 offset:3072
	ds_read_b128 v[234:237], v185 offset:4096
	ds_read_b128 v[238:241], v185 offset:5120
	ds_read_b128 v[244:247], v185 offset:6144
	ds_read_b128 v[248:251], v185 offset:7168
	global_load_lds_dwordx4 v[170:171], off
	v_lshl_add_u64 v[170:171], s[58:59], 0, v[158:159]
	s_add_i32 m0, s65, 0xe000
	s_nop 0
	global_load_lds_dwordx4 v[170:171], off
	s_waitcnt vmcnt(8)
	s_waitcnt lgkmcnt(0)
	s_barrier
	s_setprio 1
	s_waitcnt lgkmcnt(0)
	v_mfma_f32_16x16x32_bf16 v[124:127], v[128:131], v[218:221], v[124:127]
	v_mfma_f32_16x16x32_bf16 v[124:127], v[132:135], v[222:225], v[124:127]
	v_mfma_f32_16x16x32_bf16 v[108:111], v[128:131], v[226:229], v[108:111]
	v_mfma_f32_16x16x32_bf16 v[108:111], v[132:135], v[230:233], v[108:111]
	v_mfma_f32_16x16x32_bf16 v[92:95], v[128:131], v[234:237], v[92:95]
	v_mfma_f32_16x16x32_bf16 v[92:95], v[132:135], v[238:241], v[92:95]
	v_mfma_f32_16x16x32_bf16 v[76:79], v[128:131], v[244:247], v[76:79]
	v_mfma_f32_16x16x32_bf16 v[76:79], v[132:135], v[248:251], v[76:79]
	v_mfma_f32_16x16x32_bf16 v[72:75], v[164:167], v[244:247], v[72:75]
	v_mfma_f32_16x16x32_bf16 v[72:75], v[194:197], v[248:251], v[72:75]
	v_mfma_f32_16x16x32_bf16 v[88:91], v[164:167], v[234:237], v[88:91]
	v_mfma_f32_16x16x32_bf16 v[88:91], v[194:197], v[238:241], v[88:91]
	v_mfma_f32_16x16x32_bf16 v[104:107], v[164:167], v[226:229], v[104:107]
	v_mfma_f32_16x16x32_bf16 v[104:107], v[194:197], v[230:233], v[104:107]
	v_mfma_f32_16x16x32_bf16 v[120:123], v[164:167], v[218:221], v[120:123]
	v_mfma_f32_16x16x32_bf16 v[120:123], v[194:197], v[222:225], v[120:123]
	v_mfma_f32_16x16x32_bf16 v[116:119], v[198:201], v[218:221], v[116:119]
	v_mfma_f32_16x16x32_bf16 v[116:119], v[202:205], v[222:225], v[116:119]
	v_mfma_f32_16x16x32_bf16 v[100:103], v[198:201], v[226:229], v[100:103]
	v_mfma_f32_16x16x32_bf16 v[100:103], v[202:205], v[230:233], v[100:103]
	v_mfma_f32_16x16x32_bf16 v[84:87], v[198:201], v[234:237], v[84:87]
	v_mfma_f32_16x16x32_bf16 v[84:87], v[202:205], v[238:241], v[84:87]
	v_mfma_f32_16x16x32_bf16 v[68:71], v[198:201], v[244:247], v[68:71]
	v_mfma_f32_16x16x32_bf16 v[68:71], v[202:205], v[248:251], v[68:71]
	v_mfma_f32_16x16x32_bf16 v[64:67], v[206:209], v[244:247], v[64:67]
	v_mfma_f32_16x16x32_bf16 v[64:67], v[214:217], v[248:251], v[64:67]
	v_mfma_f32_16x16x32_bf16 v[80:83], v[206:209], v[234:237], v[80:83]
	v_mfma_f32_16x16x32_bf16 v[80:83], v[214:217], v[238:241], v[80:83]
	v_mfma_f32_16x16x32_bf16 v[96:99], v[206:209], v[226:229], v[96:99]
	v_mfma_f32_16x16x32_bf16 v[96:99], v[214:217], v[230:233], v[96:99]
	v_mfma_f32_16x16x32_bf16 v[112:115], v[206:209], v[218:221], v[112:115]
	v_mfma_f32_16x16x32_bf16 v[112:115], v[214:217], v[222:225], v[112:115]
	s_setprio 0
	s_barrier
	s_add_i32 s20, s89, s64
	v_lshl_add_u64 v[170:171], s[60:61], 0, v[138:139]
	s_mov_b32 m0, s20
	ds_read_b128 v[218:221], v185 offset:16384
	ds_read_b128 v[222:225], v185 offset:17408
	ds_read_b128 v[226:229], v185 offset:18432
	ds_read_b128 v[230:233], v185 offset:19456
	ds_read_b128 v[234:237], v185 offset:20480
	ds_read_b128 v[238:241], v185 offset:21504
	ds_read_b128 v[244:247], v185 offset:22528
	ds_read_b128 v[248:251], v185 offset:23552
	global_load_lds_dwordx4 v[170:171], off
	s_add_i32 m0, s20, 0x2000
	s_add_u32 s20, s60, 0x40000
	v_lshl_add_u64 v[174:175], s[60:61], 0, v[142:143]
	s_addc_u32 s21, s61, 0
	s_add_i32 s33, s90, s64
	global_load_lds_dwordx4 v[174:175], off
	v_lshl_add_u64 v[178:179], s[20:21], 0, v[138:139]
	s_mov_b32 m0, s33
	v_lshl_add_u64 v[182:183], s[62:63], 0, v[140:141]
	global_load_lds_dwordx4 v[178:179], off
	v_lshl_add_u64 v[178:179], s[20:21], 0, v[142:143]
	s_add_i32 m0, s33, 0x2000
	s_nop 0
	global_load_lds_dwordx4 v[178:179], off
	v_lshl_add_u64 v[178:179], s[62:63], 0, v[136:137]
	s_mov_b32 m0, s65
	s_nop 0
	global_load_lds_dwordx4 v[178:179], off
	s_mov_b32 m0, s76
	s_nop 0
	global_load_lds_dwordx4 v[182:183], off
	s_waitcnt vmcnt(8)
	s_waitcnt lgkmcnt(0)
	s_barrier
	s_setprio 1
	s_waitcnt lgkmcnt(0)
	v_mfma_f32_16x16x32_bf16 v[60:63], v[128:131], v[218:221], v[60:63]
	v_mfma_f32_16x16x32_bf16 v[60:63], v[132:135], v[222:225], v[60:63]
	v_mfma_f32_16x16x32_bf16 v[44:47], v[128:131], v[226:229], v[44:47]
	v_mfma_f32_16x16x32_bf16 v[44:47], v[132:135], v[230:233], v[44:47]
	v_mfma_f32_16x16x32_bf16 v[28:31], v[128:131], v[234:237], v[28:31]
	v_mfma_f32_16x16x32_bf16 v[28:31], v[132:135], v[238:241], v[28:31]
	v_mfma_f32_16x16x32_bf16 v[12:15], v[128:131], v[244:247], v[12:15]
	v_mfma_f32_16x16x32_bf16 v[12:15], v[132:135], v[248:251], v[12:15]
	v_mfma_f32_16x16x32_bf16 v[8:11], v[164:167], v[244:247], v[8:11]
	v_mfma_f32_16x16x32_bf16 v[8:11], v[194:197], v[248:251], v[8:11]
	v_mfma_f32_16x16x32_bf16 v[24:27], v[164:167], v[234:237], v[24:27]
	v_mfma_f32_16x16x32_bf16 v[24:27], v[194:197], v[238:241], v[24:27]
	v_mfma_f32_16x16x32_bf16 v[40:43], v[164:167], v[226:229], v[40:43]
	v_mfma_f32_16x16x32_bf16 v[40:43], v[194:197], v[230:233], v[40:43]
	v_mfma_f32_16x16x32_bf16 v[56:59], v[164:167], v[218:221], v[56:59]
	v_mfma_f32_16x16x32_bf16 v[56:59], v[194:197], v[222:225], v[56:59]
	v_mfma_f32_16x16x32_bf16 v[52:55], v[198:201], v[218:221], v[52:55]
	v_mfma_f32_16x16x32_bf16 v[52:55], v[202:205], v[222:225], v[52:55]
	v_mfma_f32_16x16x32_bf16 v[36:39], v[198:201], v[226:229], v[36:39]
	v_mfma_f32_16x16x32_bf16 v[36:39], v[202:205], v[230:233], v[36:39]
	v_mfma_f32_16x16x32_bf16 v[20:23], v[198:201], v[234:237], v[20:23]
	v_mfma_f32_16x16x32_bf16 v[20:23], v[202:205], v[238:241], v[20:23]
	v_mfma_f32_16x16x32_bf16 v[4:7], v[198:201], v[244:247], v[4:7]
	v_mfma_f32_16x16x32_bf16 v[4:7], v[202:205], v[248:251], v[4:7]
	v_mfma_f32_16x16x32_bf16 v[0:3], v[206:209], v[244:247], v[0:3]
	v_mfma_f32_16x16x32_bf16 v[0:3], v[214:217], v[248:251], v[0:3]
	v_mfma_f32_16x16x32_bf16 v[16:19], v[206:209], v[234:237], v[16:19]
	v_mfma_f32_16x16x32_bf16 v[16:19], v[214:217], v[238:241], v[16:19]
	v_mfma_f32_16x16x32_bf16 v[32:35], v[206:209], v[226:229], v[32:35]
	v_mfma_f32_16x16x32_bf16 v[32:35], v[214:217], v[230:233], v[32:35]
	v_mfma_f32_16x16x32_bf16 v[48:51], v[206:209], v[218:221], v[48:51]
	v_mfma_f32_16x16x32_bf16 v[48:51], v[214:217], v[222:225], v[48:51]
	s_setprio 0
	s_barrier
	s_add_i32 s33, 0, 0x18000
	v_add_u32_e32 v144, s33, v169
	s_add_i32 s75, 0, 0x1c000
	ds_read_b128 v[128:131], v144
	ds_read_b128 v[132:135], v144 offset:1024
	ds_read_b128 v[164:167], v144 offset:2048
	ds_read_b128 v[194:197], v144 offset:3072
	v_add_u32_e32 v144, s75, v169
	ds_read_b128 v[198:201], v144
	ds_read_b128 v[202:205], v144 offset:1024
	ds_read_b128 v[206:209], v144 offset:2048
	ds_read_b128 v[214:217], v144 offset:3072
	s_add_u32 s20, s62, 0x40000
	s_addc_u32 s21, s63, 0
	s_mov_b32 m0, s77
	v_lshl_add_u64 v[186:187], s[20:21], 0, v[136:137]
	ds_read_b128 v[218:221], v185 offset:32768
	ds_read_b128 v[222:225], v185 offset:33792
	ds_read_b128 v[226:229], v185 offset:34816
	ds_read_b128 v[230:233], v185 offset:35840
	ds_read_b128 v[234:237], v185 offset:36864
	ds_read_b128 v[238:241], v185 offset:37888
	ds_read_b128 v[244:247], v185 offset:38912
	ds_read_b128 v[248:251], v185 offset:39936
	global_load_lds_dwordx4 v[186:187], off
	v_lshl_add_u64 v[186:187], s[20:21], 0, v[140:141]
	s_mov_b32 m0, s78
	s_nop 0
	global_load_lds_dwordx4 v[186:187], off
	s_waitcnt vmcnt(8)
	s_waitcnt lgkmcnt(0)
	s_barrier
	s_setprio 1
	s_waitcnt lgkmcnt(0)
	v_mfma_f32_16x16x32_bf16 v[124:127], v[128:131], v[218:221], v[124:127]
	v_mfma_f32_16x16x32_bf16 v[124:127], v[132:135], v[222:225], v[124:127]
	v_mfma_f32_16x16x32_bf16 v[108:111], v[128:131], v[226:229], v[108:111]
	v_mfma_f32_16x16x32_bf16 v[108:111], v[132:135], v[230:233], v[108:111]
	v_mfma_f32_16x16x32_bf16 v[92:95], v[128:131], v[234:237], v[92:95]
	v_mfma_f32_16x16x32_bf16 v[92:95], v[132:135], v[238:241], v[92:95]
	v_mfma_f32_16x16x32_bf16 v[76:79], v[128:131], v[244:247], v[76:79]
	v_mfma_f32_16x16x32_bf16 v[76:79], v[132:135], v[248:251], v[76:79]
	v_mfma_f32_16x16x32_bf16 v[72:75], v[164:167], v[244:247], v[72:75]
	v_mfma_f32_16x16x32_bf16 v[72:75], v[194:197], v[248:251], v[72:75]
	v_mfma_f32_16x16x32_bf16 v[88:91], v[164:167], v[234:237], v[88:91]
	v_mfma_f32_16x16x32_bf16 v[88:91], v[194:197], v[238:241], v[88:91]
	v_mfma_f32_16x16x32_bf16 v[104:107], v[164:167], v[226:229], v[104:107]
	v_mfma_f32_16x16x32_bf16 v[104:107], v[194:197], v[230:233], v[104:107]
	v_mfma_f32_16x16x32_bf16 v[120:123], v[164:167], v[218:221], v[120:123]
	v_mfma_f32_16x16x32_bf16 v[120:123], v[194:197], v[222:225], v[120:123]
	v_mfma_f32_16x16x32_bf16 v[116:119], v[198:201], v[218:221], v[116:119]
	v_mfma_f32_16x16x32_bf16 v[116:119], v[202:205], v[222:225], v[116:119]
	v_mfma_f32_16x16x32_bf16 v[100:103], v[198:201], v[226:229], v[100:103]
	v_mfma_f32_16x16x32_bf16 v[100:103], v[202:205], v[230:233], v[100:103]
	v_mfma_f32_16x16x32_bf16 v[84:87], v[198:201], v[234:237], v[84:87]
	v_mfma_f32_16x16x32_bf16 v[84:87], v[202:205], v[238:241], v[84:87]
	v_mfma_f32_16x16x32_bf16 v[68:71], v[198:201], v[244:247], v[68:71]
	v_mfma_f32_16x16x32_bf16 v[68:71], v[202:205], v[248:251], v[68:71]
	v_mfma_f32_16x16x32_bf16 v[64:67], v[206:209], v[244:247], v[64:67]
	v_mfma_f32_16x16x32_bf16 v[64:67], v[214:217], v[248:251], v[64:67]
	v_mfma_f32_16x16x32_bf16 v[80:83], v[206:209], v[234:237], v[80:83]
	v_mfma_f32_16x16x32_bf16 v[80:83], v[214:217], v[238:241], v[80:83]
	v_mfma_f32_16x16x32_bf16 v[96:99], v[206:209], v[226:229], v[96:99]
	v_mfma_f32_16x16x32_bf16 v[96:99], v[214:217], v[230:233], v[96:99]
	v_mfma_f32_16x16x32_bf16 v[112:115], v[206:209], v[218:221], v[112:115]
	v_mfma_f32_16x16x32_bf16 v[112:115], v[214:217], v[222:225], v[112:115]
	s_setprio 0
	s_barrier
	s_add_i32 s20, s33, s64
	v_lshl_add_u64 v[170:171], v[170:171], 0, s[12:13]
	s_mov_b32 m0, s20
	ds_read_b128 v[218:221], v185 offset:49152
	ds_read_b128 v[222:225], v185 offset:50176
	ds_read_b128 v[226:229], v185 offset:51200
	ds_read_b128 v[230:233], v185 offset:52224
	ds_read_b128 v[234:237], v185 offset:53248
	ds_read_b128 v[238:241], v185 offset:54272
	ds_read_b128 v[244:247], v185 offset:55296
	ds_read_b128 v[248:251], v185 offset:56320
	global_load_lds_dwordx4 v[170:171], off
	s_add_i32 m0, s20, 0x2000
	s_add_u32 s20, s60, 0x40080
	v_lshl_add_u64 v[170:171], v[174:175], 0, s[12:13]
	s_addc_u32 s21, s61, 0
	s_add_i32 s33, s75, s64
	global_load_lds_dwordx4 v[170:171], off
	v_lshl_add_u64 v[170:171], s[20:21], 0, v[138:139]
	s_mov_b32 m0, s33
	s_nop 0
	global_load_lds_dwordx4 v[170:171], off
	v_lshl_add_u64 v[170:171], s[20:21], 0, v[142:143]
	s_add_i32 m0, s33, 0x2000
	s_nop 0
	global_load_lds_dwordx4 v[170:171], off
	v_lshl_add_u64 v[170:171], v[178:179], 0, s[12:13]
	s_mov_b32 m0, s82
	s_nop 0
	global_load_lds_dwordx4 v[170:171], off
	v_lshl_add_u64 v[170:171], v[182:183], 0, s[12:13]
	s_mov_b32 m0, s83
	s_nop 0
	global_load_lds_dwordx4 v[170:171], off
	s_waitcnt vmcnt(8)
	s_waitcnt lgkmcnt(0)
	s_barrier
	s_setprio 1
	s_waitcnt lgkmcnt(0)
	v_mfma_f32_16x16x32_bf16 v[60:63], v[128:131], v[218:221], v[60:63]
	v_mfma_f32_16x16x32_bf16 v[60:63], v[132:135], v[222:225], v[60:63]
	v_mfma_f32_16x16x32_bf16 v[44:47], v[128:131], v[226:229], v[44:47]
	v_mfma_f32_16x16x32_bf16 v[44:47], v[132:135], v[230:233], v[44:47]
	v_mfma_f32_16x16x32_bf16 v[28:31], v[128:131], v[234:237], v[28:31]
	v_mfma_f32_16x16x32_bf16 v[28:31], v[132:135], v[238:241], v[28:31]
	v_mfma_f32_16x16x32_bf16 v[12:15], v[128:131], v[244:247], v[12:15]
	v_mfma_f32_16x16x32_bf16 v[12:15], v[132:135], v[248:251], v[12:15]
	v_mfma_f32_16x16x32_bf16 v[8:11], v[164:167], v[244:247], v[8:11]
	v_mfma_f32_16x16x32_bf16 v[8:11], v[194:197], v[248:251], v[8:11]
	v_mfma_f32_16x16x32_bf16 v[24:27], v[164:167], v[234:237], v[24:27]
	v_mfma_f32_16x16x32_bf16 v[24:27], v[194:197], v[238:241], v[24:27]
	v_mfma_f32_16x16x32_bf16 v[40:43], v[164:167], v[226:229], v[40:43]
	v_mfma_f32_16x16x32_bf16 v[40:43], v[194:197], v[230:233], v[40:43]
	v_mfma_f32_16x16x32_bf16 v[56:59], v[164:167], v[218:221], v[56:59]
	v_mfma_f32_16x16x32_bf16 v[56:59], v[194:197], v[222:225], v[56:59]
	v_mfma_f32_16x16x32_bf16 v[52:55], v[198:201], v[218:221], v[52:55]
	v_mfma_f32_16x16x32_bf16 v[52:55], v[202:205], v[222:225], v[52:55]
	v_mfma_f32_16x16x32_bf16 v[36:39], v[198:201], v[226:229], v[36:39]
	v_mfma_f32_16x16x32_bf16 v[36:39], v[202:205], v[230:233], v[36:39]
	v_mfma_f32_16x16x32_bf16 v[20:23], v[198:201], v[234:237], v[20:23]
	v_mfma_f32_16x16x32_bf16 v[20:23], v[202:205], v[238:241], v[20:23]
	v_mfma_f32_16x16x32_bf16 v[4:7], v[198:201], v[244:247], v[4:7]
	v_mfma_f32_16x16x32_bf16 v[4:7], v[202:205], v[248:251], v[4:7]
	v_mfma_f32_16x16x32_bf16 v[0:3], v[206:209], v[244:247], v[0:3]
	v_mfma_f32_16x16x32_bf16 v[0:3], v[214:217], v[248:251], v[0:3]
	v_mfma_f32_16x16x32_bf16 v[16:19], v[206:209], v[234:237], v[16:19]
	v_mfma_f32_16x16x32_bf16 v[16:19], v[214:217], v[238:241], v[16:19]
	v_mfma_f32_16x16x32_bf16 v[32:35], v[206:209], v[226:229], v[32:35]
	v_mfma_f32_16x16x32_bf16 v[32:35], v[214:217], v[230:233], v[32:35]
	v_mfma_f32_16x16x32_bf16 v[48:51], v[206:209], v[218:221], v[48:51]
	v_mfma_f32_16x16x32_bf16 v[48:51], v[214:217], v[222:225], v[48:51]
	s_setprio 0
	s_barrier
	s_add_i32 s97, s97, 2
	s_add_u32 s58, s58, 0x100
	s_addc_u32 s59, s59, 0
	s_add_u32 s95, s95, 0x100
	s_addc_u32 s96, s96, 0
	s_cmp_gt_u32 s97, 13
	s_cbranch_scc0 .LBB0_287
	s_and_b64 vcc, exec, s[14:15]
	s_cbranch_vccz .LBB0_290
	s_barrier

.LBB0_637:
	ds_read_b128 v[112:115], v247
	ds_read_b128 v[116:119], v247 offset:1024
	ds_read_b128 v[124:127], v247 offset:2048
	ds_read_b128 v[128:131], v247 offset:3072
	ds_read_b128 v[132:135], v248
	ds_read_b128 v[140:143], v248 offset:1024
	ds_read_b128 v[144:147], v248 offset:2048
	ds_read_b128 v[152:155], v248 offset:3072
	s_add_u32 s20, s44, 0xfffc0080
	s_addc_u32 s21, s45, -1
	s_cmp_eq_u32 s75, 12
	s_cselect_b32 s51, s19, s21
	s_cselect_b32 s50, s43, s20
	s_cselect_b32 s49, s17, s74
	s_cselect_b32 s48, s66, s67
	v_lshl_add_u64 v[206:207], s[44:45], 0, v[200:201]
	s_add_i32 m0, s53, 0xc000
	ds_read_b128 v[160:163], v249
	ds_read_b128 v[164:167], v249 offset:1024
	ds_read_b128 v[168:171], v249 offset:2048
	ds_read_b128 v[172:175], v249 offset:3072
	ds_read_b128 v[176:179], v249 offset:4096
	ds_read_b128 v[180:183], v249 offset:5120
	ds_read_b128 v[184:187], v249 offset:6144
	ds_read_b128 v[188:191], v249 offset:7168
	global_load_lds_dwordx4 v[206:207], off
	v_lshl_add_u64 v[206:207], s[44:45], 0, v[202:203]
	s_add_i32 m0, s53, 0xe000
	s_nop 0
	global_load_lds_dwordx4 v[206:207], off
	s_waitcnt vmcnt(8)
	s_waitcnt lgkmcnt(0)
	s_barrier
	s_setprio 1
	s_waitcnt lgkmcnt(0)
	v_mfma_f32_16x16x32_bf16 v[156:159], v[112:115], v[160:163], v[156:159]
	v_mfma_f32_16x16x32_bf16 v[156:159], v[116:119], v[164:167], v[156:159]
	v_mfma_f32_16x16x32_bf16 v[108:111], v[112:115], v[168:171], v[108:111]
	v_mfma_f32_16x16x32_bf16 v[108:111], v[116:119], v[172:175], v[108:111]
	v_mfma_f32_16x16x32_bf16 v[92:95], v[112:115], v[176:179], v[92:95]
	v_mfma_f32_16x16x32_bf16 v[92:95], v[116:119], v[180:183], v[92:95]
	v_mfma_f32_16x16x32_bf16 v[76:79], v[112:115], v[184:187], v[76:79]
	v_mfma_f32_16x16x32_bf16 v[76:79], v[116:119], v[188:191], v[76:79]
	v_mfma_f32_16x16x32_bf16 v[72:75], v[124:127], v[184:187], v[72:75]
	v_mfma_f32_16x16x32_bf16 v[72:75], v[128:131], v[188:191], v[72:75]
	v_mfma_f32_16x16x32_bf16 v[88:91], v[124:127], v[176:179], v[88:91]
	v_mfma_f32_16x16x32_bf16 v[88:91], v[128:131], v[180:183], v[88:91]
	v_mfma_f32_16x16x32_bf16 v[104:107], v[124:127], v[168:171], v[104:107]
	v_mfma_f32_16x16x32_bf16 v[104:107], v[128:131], v[172:175], v[104:107]
	v_mfma_f32_16x16x32_bf16 v[148:151], v[124:127], v[160:163], v[148:151]
	v_mfma_f32_16x16x32_bf16 v[148:151], v[128:131], v[164:167], v[148:151]
	v_mfma_f32_16x16x32_bf16 v[136:139], v[132:135], v[160:163], v[136:139]
	v_mfma_f32_16x16x32_bf16 v[136:139], v[140:143], v[164:167], v[136:139]
	v_mfma_f32_16x16x32_bf16 v[100:103], v[132:135], v[168:171], v[100:103]
	v_mfma_f32_16x16x32_bf16 v[100:103], v[140:143], v[172:175], v[100:103]
	v_mfma_f32_16x16x32_bf16 v[84:87], v[132:135], v[176:179], v[84:87]
	v_mfma_f32_16x16x32_bf16 v[84:87], v[140:143], v[180:183], v[84:87]
	v_mfma_f32_16x16x32_bf16 v[68:71], v[132:135], v[184:187], v[68:71]
	v_mfma_f32_16x16x32_bf16 v[68:71], v[140:143], v[188:191], v[68:71]
	v_mfma_f32_16x16x32_bf16 v[64:67], v[144:147], v[184:187], v[64:67]
	v_mfma_f32_16x16x32_bf16 v[64:67], v[152:155], v[188:191], v[64:67]
	v_mfma_f32_16x16x32_bf16 v[80:83], v[144:147], v[176:179], v[80:83]
	v_mfma_f32_16x16x32_bf16 v[80:83], v[152:155], v[180:183], v[80:83]
	v_mfma_f32_16x16x32_bf16 v[96:99], v[144:147], v[168:171], v[96:99]
	v_mfma_f32_16x16x32_bf16 v[96:99], v[152:155], v[172:175], v[96:99]
	v_mfma_f32_16x16x32_bf16 v[120:123], v[144:147], v[160:163], v[120:123]
	v_mfma_f32_16x16x32_bf16 v[120:123], v[152:155], v[164:167], v[120:123]
	s_setprio 0
	s_barrier
	s_add_i32 s20, s63, s52
	v_lshl_add_u64 v[206:207], s[48:49], 0, v[194:195]
	s_mov_b32 m0, s20
	ds_read_b128 v[160:163], v249 offset:16384
	ds_read_b128 v[164:167], v249 offset:17408
	ds_read_b128 v[168:171], v249 offset:18432
	ds_read_b128 v[172:175], v249 offset:19456
	ds_read_b128 v[176:179], v249 offset:20480
	ds_read_b128 v[180:183], v249 offset:21504
	ds_read_b128 v[184:187], v249 offset:22528
	ds_read_b128 v[188:191], v249 offset:23552
	global_load_lds_dwordx4 v[206:207], off
	s_add_i32 m0, s20, 0x2000
	s_add_u32 s20, s48, 0x40000
	v_lshl_add_u64 v[208:209], s[48:49], 0, v[198:199]
	s_addc_u32 s21, s49, 0
	s_add_i32 s33, s64, s52
	global_load_lds_dwordx4 v[208:209], off
	v_lshl_add_u64 v[210:211], s[20:21], 0, v[194:195]
	s_mov_b32 m0, s33
	v_lshl_add_u64 v[212:213], s[50:51], 0, v[196:197]
	global_load_lds_dwordx4 v[210:211], off
	v_lshl_add_u64 v[210:211], s[20:21], 0, v[198:199]
	s_add_i32 m0, s33, 0x2000
	s_nop 0
	global_load_lds_dwordx4 v[210:211], off
	v_lshl_add_u64 v[210:211], s[50:51], 0, v[192:193]
	s_mov_b32 m0, s53
	s_nop 0
	global_load_lds_dwordx4 v[210:211], off
	s_mov_b32 m0, s54
	s_nop 0
	global_load_lds_dwordx4 v[212:213], off
	s_waitcnt vmcnt(8)
	s_waitcnt lgkmcnt(0)
	s_barrier
	s_setprio 1
	s_waitcnt lgkmcnt(0)
	v_mfma_f32_16x16x32_bf16 v[60:63], v[112:115], v[160:163], v[60:63]
	v_mfma_f32_16x16x32_bf16 v[60:63], v[116:119], v[164:167], v[60:63]
	v_mfma_f32_16x16x32_bf16 v[44:47], v[112:115], v[168:171], v[44:47]
	v_mfma_f32_16x16x32_bf16 v[44:47], v[116:119], v[172:175], v[44:47]
	v_mfma_f32_16x16x32_bf16 v[28:31], v[112:115], v[176:179], v[28:31]
	v_mfma_f32_16x16x32_bf16 v[28:31], v[116:119], v[180:183], v[28:31]
	v_mfma_f32_16x16x32_bf16 v[12:15], v[112:115], v[184:187], v[12:15]
	v_mfma_f32_16x16x32_bf16 v[12:15], v[116:119], v[188:191], v[12:15]
	v_mfma_f32_16x16x32_bf16 v[8:11], v[124:127], v[184:187], v[8:11]
	v_mfma_f32_16x16x32_bf16 v[8:11], v[128:131], v[188:191], v[8:11]
	v_mfma_f32_16x16x32_bf16 v[24:27], v[124:127], v[176:179], v[24:27]
	v_mfma_f32_16x16x32_bf16 v[24:27], v[128:131], v[180:183], v[24:27]
	v_mfma_f32_16x16x32_bf16 v[40:43], v[124:127], v[168:171], v[40:43]
	v_mfma_f32_16x16x32_bf16 v[40:43], v[128:131], v[172:175], v[40:43]
	v_mfma_f32_16x16x32_bf16 v[56:59], v[124:127], v[160:163], v[56:59]
	v_mfma_f32_16x16x32_bf16 v[56:59], v[128:131], v[164:167], v[56:59]
	v_mfma_f32_16x16x32_bf16 v[52:55], v[132:135], v[160:163], v[52:55]
	v_mfma_f32_16x16x32_bf16 v[52:55], v[140:143], v[164:167], v[52:55]
	v_mfma_f32_16x16x32_bf16 v[36:39], v[132:135], v[168:171], v[36:39]
	v_mfma_f32_16x16x32_bf16 v[36:39], v[140:143], v[172:175], v[36:39]
	v_mfma_f32_16x16x32_bf16 v[20:23], v[132:135], v[176:179], v[20:23]
	v_mfma_f32_16x16x32_bf16 v[20:23], v[140:143], v[180:183], v[20:23]
	v_mfma_f32_16x16x32_bf16 v[4:7], v[132:135], v[184:187], v[4:7]
	v_mfma_f32_16x16x32_bf16 v[4:7], v[140:143], v[188:191], v[4:7]
	v_mfma_f32_16x16x32_bf16 v[0:3], v[144:147], v[184:187], v[0:3]
	v_mfma_f32_16x16x32_bf16 v[0:3], v[152:155], v[188:191], v[0:3]
	v_mfma_f32_16x16x32_bf16 v[16:19], v[144:147], v[176:179], v[16:19]
	v_mfma_f32_16x16x32_bf16 v[16:19], v[152:155], v[180:183], v[16:19]
	v_mfma_f32_16x16x32_bf16 v[32:35], v[144:147], v[168:171], v[32:35]
	v_mfma_f32_16x16x32_bf16 v[32:35], v[152:155], v[172:175], v[32:35]
	v_mfma_f32_16x16x32_bf16 v[48:51], v[144:147], v[160:163], v[48:51]
	v_mfma_f32_16x16x32_bf16 v[48:51], v[152:155], v[164:167], v[48:51]
	s_setprio 0
	s_barrier
	s_add_i32 s33, 0, 0x18000
	s_add_i32 s76, 0, 0x1c000
	v_add_u32_e32 v128, s33, v245
	v_add_u32_e32 v152, s76, v245
	ds_read_b128 v[112:115], v128
	ds_read_b128 v[116:119], v128 offset:1024
	ds_read_b128 v[124:127], v128 offset:2048
	ds_read_b128 v[128:131], v128 offset:3072
	ds_read_b128 v[132:135], v152
	ds_read_b128 v[140:143], v152 offset:1024
	ds_read_b128 v[144:147], v152 offset:2048
	ds_read_b128 v[152:155], v152 offset:3072
	s_add_u32 s20, s50, 0x40000
	s_addc_u32 s21, s51, 0
	s_mov_b32 m0, s55
	v_lshl_add_u64 v[214:215], s[20:21], 0, v[192:193]
	ds_read_b128 v[160:163], v249 offset:32768
	ds_read_b128 v[164:167], v249 offset:33792
	ds_read_b128 v[168:171], v249 offset:34816
	ds_read_b128 v[172:175], v249 offset:35840
	ds_read_b128 v[176:179], v249 offset:36864
	ds_read_b128 v[180:183], v249 offset:37888
	ds_read_b128 v[184:187], v249 offset:38912
	ds_read_b128 v[188:191], v249 offset:39936
	global_load_lds_dwordx4 v[214:215], off
	v_lshl_add_u64 v[214:215], s[20:21], 0, v[196:197]
	s_mov_b32 m0, s56
	s_nop 0
	global_load_lds_dwordx4 v[214:215], off
	s_waitcnt vmcnt(8)
	s_waitcnt lgkmcnt(0)
	s_barrier
	s_setprio 1
	s_waitcnt lgkmcnt(0)
	v_mfma_f32_16x16x32_bf16 v[156:159], v[112:115], v[160:163], v[156:159]
	v_mfma_f32_16x16x32_bf16 v[156:159], v[116:119], v[164:167], v[156:159]
	v_mfma_f32_16x16x32_bf16 v[108:111], v[112:115], v[168:171], v[108:111]
	v_mfma_f32_16x16x32_bf16 v[108:111], v[116:119], v[172:175], v[108:111]
	v_mfma_f32_16x16x32_bf16 v[92:95], v[112:115], v[176:179], v[92:95]
	v_mfma_f32_16x16x32_bf16 v[92:95], v[116:119], v[180:183], v[92:95]
	v_mfma_f32_16x16x32_bf16 v[76:79], v[112:115], v[184:187], v[76:79]
	v_mfma_f32_16x16x32_bf16 v[76:79], v[116:119], v[188:191], v[76:79]
	v_mfma_f32_16x16x32_bf16 v[72:75], v[124:127], v[184:187], v[72:75]
	v_mfma_f32_16x16x32_bf16 v[72:75], v[128:131], v[188:191], v[72:75]
	v_mfma_f32_16x16x32_bf16 v[88:91], v[124:127], v[176:179], v[88:91]
	v_mfma_f32_16x16x32_bf16 v[88:91], v[128:131], v[180:183], v[88:91]
	v_mfma_f32_16x16x32_bf16 v[104:107], v[124:127], v[168:171], v[104:107]
	v_mfma_f32_16x16x32_bf16 v[104:107], v[128:131], v[172:175], v[104:107]
	v_mfma_f32_16x16x32_bf16 v[148:151], v[124:127], v[160:163], v[148:151]
	v_mfma_f32_16x16x32_bf16 v[148:151], v[128:131], v[164:167], v[148:151]
	v_mfma_f32_16x16x32_bf16 v[136:139], v[132:135], v[160:163], v[136:139]
	v_mfma_f32_16x16x32_bf16 v[136:139], v[140:143], v[164:167], v[136:139]
	v_mfma_f32_16x16x32_bf16 v[100:103], v[132:135], v[168:171], v[100:103]
	v_mfma_f32_16x16x32_bf16 v[100:103], v[140:143], v[172:175], v[100:103]
	v_mfma_f32_16x16x32_bf16 v[84:87], v[132:135], v[176:179], v[84:87]
	v_mfma_f32_16x16x32_bf16 v[84:87], v[140:143], v[180:183], v[84:87]
	v_mfma_f32_16x16x32_bf16 v[68:71], v[132:135], v[184:187], v[68:71]
	v_mfma_f32_16x16x32_bf16 v[68:71], v[140:143], v[188:191], v[68:71]
	v_mfma_f32_16x16x32_bf16 v[64:67], v[144:147], v[184:187], v[64:67]
	v_mfma_f32_16x16x32_bf16 v[64:67], v[152:155], v[188:191], v[64:67]
	v_mfma_f32_16x16x32_bf16 v[80:83], v[144:147], v[176:179], v[80:83]
	v_mfma_f32_16x16x32_bf16 v[80:83], v[152:155], v[180:183], v[80:83]
	v_mfma_f32_16x16x32_bf16 v[96:99], v[144:147], v[168:171], v[96:99]
	v_mfma_f32_16x16x32_bf16 v[96:99], v[152:155], v[172:175], v[96:99]
	v_mfma_f32_16x16x32_bf16 v[120:123], v[144:147], v[160:163], v[120:123]
	v_mfma_f32_16x16x32_bf16 v[120:123], v[152:155], v[164:167], v[120:123]
	s_setprio 0
	s_barrier
	s_add_i32 s20, s33, s52
	v_lshl_add_u64 v[206:207], v[206:207], 0, s[12:13]
	s_mov_b32 m0, s20
	ds_read_b128 v[160:163], v249 offset:49152
	ds_read_b128 v[164:167], v249 offset:50176
	ds_read_b128 v[168:171], v249 offset:51200
	ds_read_b128 v[172:175], v249 offset:52224
	ds_read_b128 v[176:179], v249 offset:53248
	ds_read_b128 v[180:183], v249 offset:54272
	ds_read_b128 v[184:187], v249 offset:55296
	ds_read_b128 v[188:191], v249 offset:56320
	global_load_lds_dwordx4 v[206:207], off
	s_add_i32 m0, s20, 0x2000
	s_add_u32 s20, s48, 0x40080
	v_lshl_add_u64 v[206:207], v[208:209], 0, s[12:13]
	s_addc_u32 s21, s49, 0
	s_add_i32 s33, s76, s52
	global_load_lds_dwordx4 v[206:207], off
	v_lshl_add_u64 v[206:207], s[20:21], 0, v[194:195]
	s_mov_b32 m0, s33
	s_nop 0
	global_load_lds_dwordx4 v[206:207], off
	v_lshl_add_u64 v[206:207], s[20:21], 0, v[198:199]
	s_add_i32 m0, s33, 0x2000
	s_nop 0
	global_load_lds_dwordx4 v[206:207], off
	v_lshl_add_u64 v[206:207], v[210:211], 0, s[12:13]
	s_mov_b32 m0, s58
	s_nop 0
	global_load_lds_dwordx4 v[206:207], off
	v_lshl_add_u64 v[206:207], v[212:213], 0, s[12:13]
	s_mov_b32 m0, s59
	s_nop 0
	global_load_lds_dwordx4 v[206:207], off
	s_waitcnt vmcnt(8)
	s_waitcnt lgkmcnt(0)
	s_barrier
	s_setprio 1
	s_waitcnt lgkmcnt(0)
	v_mfma_f32_16x16x32_bf16 v[60:63], v[112:115], v[160:163], v[60:63]
	v_mfma_f32_16x16x32_bf16 v[60:63], v[116:119], v[164:167], v[60:63]
	v_mfma_f32_16x16x32_bf16 v[44:47], v[112:115], v[168:171], v[44:47]
	v_mfma_f32_16x16x32_bf16 v[44:47], v[116:119], v[172:175], v[44:47]
	v_mfma_f32_16x16x32_bf16 v[28:31], v[112:115], v[176:179], v[28:31]
	v_mfma_f32_16x16x32_bf16 v[28:31], v[116:119], v[180:183], v[28:31]
	v_mfma_f32_16x16x32_bf16 v[12:15], v[112:115], v[184:187], v[12:15]
	v_mfma_f32_16x16x32_bf16 v[12:15], v[116:119], v[188:191], v[12:15]
	v_mfma_f32_16x16x32_bf16 v[8:11], v[124:127], v[184:187], v[8:11]
	v_mfma_f32_16x16x32_bf16 v[8:11], v[128:131], v[188:191], v[8:11]
	v_mfma_f32_16x16x32_bf16 v[24:27], v[124:127], v[176:179], v[24:27]
	v_mfma_f32_16x16x32_bf16 v[24:27], v[128:131], v[180:183], v[24:27]
	v_mfma_f32_16x16x32_bf16 v[40:43], v[124:127], v[168:171], v[40:43]
	v_mfma_f32_16x16x32_bf16 v[40:43], v[128:131], v[172:175], v[40:43]
	v_mfma_f32_16x16x32_bf16 v[56:59], v[124:127], v[160:163], v[56:59]
	v_mfma_f32_16x16x32_bf16 v[56:59], v[128:131], v[164:167], v[56:59]
	v_mfma_f32_16x16x32_bf16 v[52:55], v[132:135], v[160:163], v[52:55]
	v_mfma_f32_16x16x32_bf16 v[52:55], v[140:143], v[164:167], v[52:55]
	v_mfma_f32_16x16x32_bf16 v[36:39], v[132:135], v[168:171], v[36:39]
	v_mfma_f32_16x16x32_bf16 v[36:39], v[140:143], v[172:175], v[36:39]
	v_mfma_f32_16x16x32_bf16 v[20:23], v[132:135], v[176:179], v[20:23]
	v_mfma_f32_16x16x32_bf16 v[20:23], v[140:143], v[180:183], v[20:23]
	v_mfma_f32_16x16x32_bf16 v[4:7], v[132:135], v[184:187], v[4:7]
	v_mfma_f32_16x16x32_bf16 v[4:7], v[140:143], v[188:191], v[4:7]
	v_mfma_f32_16x16x32_bf16 v[0:3], v[144:147], v[184:187], v[0:3]
	v_mfma_f32_16x16x32_bf16 v[0:3], v[152:155], v[188:191], v[0:3]
	v_mfma_f32_16x16x32_bf16 v[16:19], v[144:147], v[176:179], v[16:19]
	v_mfma_f32_16x16x32_bf16 v[16:19], v[152:155], v[180:183], v[16:19]
	v_mfma_f32_16x16x32_bf16 v[32:35], v[144:147], v[168:171], v[32:35]
	v_mfma_f32_16x16x32_bf16 v[32:35], v[152:155], v[172:175], v[32:35]
	v_mfma_f32_16x16x32_bf16 v[48:51], v[144:147], v[160:163], v[48:51]
	v_mfma_f32_16x16x32_bf16 v[48:51], v[152:155], v[164:167], v[48:51]
	s_setprio 0
	s_barrier
	s_add_i32 s75, s75, 2
	s_add_u32 s44, s44, 0x100
	s_addc_u32 s45, s45, 0
	s_add_u32 s67, s67, 0x100
	s_addc_u32 s74, s74, 0
	s_cmp_gt_u32 s75, 13
	s_cbranch_scc0 .LBB0_637
	s_and_b64 vcc, exec, s[14:15]
	s_cbranch_vccz .LBB0_640
	s_barrier

.LBB0_721:
	ds_read_b128 v[146:149], v163
	ds_read_b128 v[152:155], v163 offset:1024
	ds_read_b128 v[172:175], v163 offset:2048
	ds_read_b128 v[178:181], v163 offset:3072
	ds_read_b128 v[182:185], v167
	ds_read_b128 v[186:189], v167 offset:1024
	ds_read_b128 v[190:193], v167 offset:2048
	ds_read_b128 v[194:197], v167 offset:3072
	s_add_u32 s20, s36, 0xfffc0080
	s_addc_u32 s21, s37, -1
	s_cmp_eq_u32 s61, 12
	s_cselect_b32 s41, s13, s21
	s_cselect_b32 s40, s57, s20
	s_cselect_b32 s39, s1, s60
	s_cselect_b32 s38, s58, s59
	v_lshl_add_u64 v[158:159], s[36:37], 0, v[138:139]
	s_add_i32 m0, s19, 0xc000
	ds_read_b128 v[198:201], v171
	ds_read_b128 v[202:205], v171 offset:1024
	ds_read_b128 v[206:209], v171 offset:2048
	ds_read_b128 v[210:213], v171 offset:3072
	ds_read_b128 v[214:217], v171 offset:4096
	ds_read_b128 v[218:221], v171 offset:5120
	ds_read_b128 v[222:225], v171 offset:6144
	ds_read_b128 v[226:229], v171 offset:7168
	global_load_lds_dwordx4 v[158:159], off
	v_lshl_add_u64 v[158:159], s[36:37], 0, v[140:141]
	s_add_i32 m0, s19, 0xe000
	s_nop 0
	global_load_lds_dwordx4 v[158:159], off
	s_waitcnt vmcnt(8)
	s_waitcnt lgkmcnt(0)
	s_barrier
	s_setprio 1
	s_waitcnt lgkmcnt(0)
	v_mfma_f32_16x16x32_bf16 v[124:127], v[146:149], v[198:201], v[124:127]
	v_mfma_f32_16x16x32_bf16 v[124:127], v[152:155], v[202:205], v[124:127]
	v_mfma_f32_16x16x32_bf16 v[108:111], v[146:149], v[206:209], v[108:111]
	v_mfma_f32_16x16x32_bf16 v[108:111], v[152:155], v[210:213], v[108:111]
	v_mfma_f32_16x16x32_bf16 v[92:95], v[146:149], v[214:217], v[92:95]
	v_mfma_f32_16x16x32_bf16 v[92:95], v[152:155], v[218:221], v[92:95]
	v_mfma_f32_16x16x32_bf16 v[76:79], v[146:149], v[222:225], v[76:79]
	v_mfma_f32_16x16x32_bf16 v[76:79], v[152:155], v[226:229], v[76:79]
	v_mfma_f32_16x16x32_bf16 v[68:71], v[172:175], v[222:225], v[68:71]
	v_mfma_f32_16x16x32_bf16 v[68:71], v[178:181], v[226:229], v[68:71]
	v_mfma_f32_16x16x32_bf16 v[84:87], v[172:175], v[214:217], v[84:87]
	v_mfma_f32_16x16x32_bf16 v[84:87], v[178:181], v[218:221], v[84:87]
	v_mfma_f32_16x16x32_bf16 v[100:103], v[172:175], v[206:209], v[100:103]
	v_mfma_f32_16x16x32_bf16 v[100:103], v[178:181], v[210:213], v[100:103]
	v_mfma_f32_16x16x32_bf16 v[116:119], v[172:175], v[198:201], v[116:119]
	v_mfma_f32_16x16x32_bf16 v[116:119], v[178:181], v[202:205], v[116:119]
	v_mfma_f32_16x16x32_bf16 v[120:123], v[182:185], v[198:201], v[120:123]
	v_mfma_f32_16x16x32_bf16 v[120:123], v[186:189], v[202:205], v[120:123]
	v_mfma_f32_16x16x32_bf16 v[104:107], v[182:185], v[206:209], v[104:107]
	v_mfma_f32_16x16x32_bf16 v[104:107], v[186:189], v[210:213], v[104:107]
	v_mfma_f32_16x16x32_bf16 v[88:91], v[182:185], v[214:217], v[88:91]
	v_mfma_f32_16x16x32_bf16 v[88:91], v[186:189], v[218:221], v[88:91]
	v_mfma_f32_16x16x32_bf16 v[72:75], v[182:185], v[222:225], v[72:75]
	v_mfma_f32_16x16x32_bf16 v[72:75], v[186:189], v[226:229], v[72:75]
	v_mfma_f32_16x16x32_bf16 v[64:67], v[190:193], v[222:225], v[64:67]
	v_mfma_f32_16x16x32_bf16 v[64:67], v[194:197], v[226:229], v[64:67]
	v_mfma_f32_16x16x32_bf16 v[80:83], v[190:193], v[214:217], v[80:83]
	v_mfma_f32_16x16x32_bf16 v[80:83], v[194:197], v[218:221], v[80:83]
	v_mfma_f32_16x16x32_bf16 v[96:99], v[190:193], v[206:209], v[96:99]
	v_mfma_f32_16x16x32_bf16 v[96:99], v[194:197], v[210:213], v[96:99]
	v_mfma_f32_16x16x32_bf16 v[112:115], v[190:193], v[198:201], v[112:115]
	v_mfma_f32_16x16x32_bf16 v[112:115], v[194:197], v[202:205], v[112:115]
	s_setprio 0
	s_barrier
	s_add_i32 s20, s53, s42
	v_lshl_add_u64 v[158:159], s[38:39], 0, v[132:133]
	s_mov_b32 m0, s20
	ds_read_b128 v[198:201], v171 offset:16384
	ds_read_b128 v[202:205], v171 offset:17408
	ds_read_b128 v[206:209], v171 offset:18432
	ds_read_b128 v[210:213], v171 offset:19456
	ds_read_b128 v[214:217], v171 offset:20480
	ds_read_b128 v[218:221], v171 offset:21504
	ds_read_b128 v[222:225], v171 offset:22528
	ds_read_b128 v[226:229], v171 offset:23552
	global_load_lds_dwordx4 v[158:159], off
	s_add_i32 m0, s20, 0x2000
	s_add_u32 s20, s38, 0x40000
	v_lshl_add_u64 v[164:165], s[38:39], 0, v[128:129]
	s_addc_u32 s21, s39, 0
	s_add_i32 s33, s54, s42
	global_load_lds_dwordx4 v[164:165], off
	v_lshl_add_u64 v[168:169], s[20:21], 0, v[132:133]
	s_mov_b32 m0, s33
	v_lshl_add_u64 v[230:231], s[40:41], 0, v[130:131]
	global_load_lds_dwordx4 v[168:169], off
	v_lshl_add_u64 v[168:169], s[20:21], 0, v[128:129]
	s_add_i32 m0, s33, 0x2000
	s_nop 0
	global_load_lds_dwordx4 v[168:169], off
	v_lshl_add_u64 v[168:169], s[40:41], 0, v[134:135]
	s_mov_b32 m0, s19
	s_nop 0
	global_load_lds_dwordx4 v[168:169], off
	s_mov_b32 m0, s45
	s_nop 0
	global_load_lds_dwordx4 v[230:231], off
	s_waitcnt vmcnt(8)
	s_waitcnt lgkmcnt(0)
	s_barrier
	s_setprio 1
	s_waitcnt lgkmcnt(0)
	v_mfma_f32_16x16x32_bf16 v[60:63], v[146:149], v[198:201], v[60:63]
	v_mfma_f32_16x16x32_bf16 v[60:63], v[152:155], v[202:205], v[60:63]
	v_mfma_f32_16x16x32_bf16 v[44:47], v[146:149], v[206:209], v[44:47]
	v_mfma_f32_16x16x32_bf16 v[44:47], v[152:155], v[210:213], v[44:47]
	v_mfma_f32_16x16x32_bf16 v[28:31], v[146:149], v[214:217], v[28:31]
	v_mfma_f32_16x16x32_bf16 v[28:31], v[152:155], v[218:221], v[28:31]
	v_mfma_f32_16x16x32_bf16 v[12:15], v[146:149], v[222:225], v[12:15]
	v_mfma_f32_16x16x32_bf16 v[12:15], v[152:155], v[226:229], v[12:15]
	v_mfma_f32_16x16x32_bf16 v[4:7], v[172:175], v[222:225], v[4:7]
	v_mfma_f32_16x16x32_bf16 v[4:7], v[178:181], v[226:229], v[4:7]
	v_mfma_f32_16x16x32_bf16 v[20:23], v[172:175], v[214:217], v[20:23]
	v_mfma_f32_16x16x32_bf16 v[20:23], v[178:181], v[218:221], v[20:23]
	v_mfma_f32_16x16x32_bf16 v[36:39], v[172:175], v[206:209], v[36:39]
	v_mfma_f32_16x16x32_bf16 v[36:39], v[178:181], v[210:213], v[36:39]
	v_mfma_f32_16x16x32_bf16 v[52:55], v[172:175], v[198:201], v[52:55]
	v_mfma_f32_16x16x32_bf16 v[52:55], v[178:181], v[202:205], v[52:55]
	v_mfma_f32_16x16x32_bf16 v[56:59], v[182:185], v[198:201], v[56:59]
	v_mfma_f32_16x16x32_bf16 v[56:59], v[186:189], v[202:205], v[56:59]
	v_mfma_f32_16x16x32_bf16 v[40:43], v[182:185], v[206:209], v[40:43]
	v_mfma_f32_16x16x32_bf16 v[40:43], v[186:189], v[210:213], v[40:43]
	v_mfma_f32_16x16x32_bf16 v[24:27], v[182:185], v[214:217], v[24:27]
	v_mfma_f32_16x16x32_bf16 v[24:27], v[186:189], v[218:221], v[24:27]
	v_mfma_f32_16x16x32_bf16 v[8:11], v[182:185], v[222:225], v[8:11]
	v_mfma_f32_16x16x32_bf16 v[8:11], v[186:189], v[226:229], v[8:11]
	v_mfma_f32_16x16x32_bf16 v[0:3], v[190:193], v[222:225], v[0:3]
	v_mfma_f32_16x16x32_bf16 v[0:3], v[194:197], v[226:229], v[0:3]
	v_mfma_f32_16x16x32_bf16 v[16:19], v[190:193], v[214:217], v[16:19]
	v_mfma_f32_16x16x32_bf16 v[16:19], v[194:197], v[218:221], v[16:19]
	v_mfma_f32_16x16x32_bf16 v[32:35], v[190:193], v[206:209], v[32:35]
	v_mfma_f32_16x16x32_bf16 v[32:35], v[194:197], v[210:213], v[32:35]
	v_mfma_f32_16x16x32_bf16 v[48:51], v[190:193], v[198:201], v[48:51]
	v_mfma_f32_16x16x32_bf16 v[48:51], v[194:197], v[202:205], v[48:51]
	s_setprio 0
	s_barrier
	s_add_i32 s33, 0, 0x18000
	v_add_u32_e32 v150, s33, v157
	s_add_i32 s62, 0, 0x1c000
	ds_read_b128 v[146:149], v150
	ds_read_b128 v[152:155], v150 offset:1024
	ds_read_b128 v[172:175], v150 offset:2048
	ds_read_b128 v[178:181], v150 offset:3072
	v_add_u32_e32 v150, s62, v157
	ds_read_b128 v[182:185], v150
	ds_read_b128 v[186:189], v150 offset:1024
	ds_read_b128 v[190:193], v150 offset:2048
	ds_read_b128 v[194:197], v150 offset:3072
	s_add_u32 s20, s40, 0x40000
	s_addc_u32 s21, s41, 0
	s_mov_b32 m0, s46
	v_lshl_add_u64 v[232:233], s[20:21], 0, v[134:135]
	ds_read_b128 v[198:201], v171 offset:32768
	ds_read_b128 v[202:205], v171 offset:33792
	ds_read_b128 v[206:209], v171 offset:34816
	ds_read_b128 v[210:213], v171 offset:35840
	ds_read_b128 v[214:217], v171 offset:36864
	ds_read_b128 v[218:221], v171 offset:37888
	ds_read_b128 v[222:225], v171 offset:38912
	ds_read_b128 v[226:229], v171 offset:39936
	global_load_lds_dwordx4 v[232:233], off
	v_lshl_add_u64 v[232:233], s[20:21], 0, v[130:131]
	s_mov_b32 m0, s47
	s_nop 0
	global_load_lds_dwordx4 v[232:233], off
	s_waitcnt vmcnt(8)
	s_waitcnt lgkmcnt(0)
	s_barrier
	s_setprio 1
	s_waitcnt lgkmcnt(0)
	v_mfma_f32_16x16x32_bf16 v[124:127], v[146:149], v[198:201], v[124:127]
	v_mfma_f32_16x16x32_bf16 v[124:127], v[152:155], v[202:205], v[124:127]
	v_mfma_f32_16x16x32_bf16 v[108:111], v[146:149], v[206:209], v[108:111]
	v_mfma_f32_16x16x32_bf16 v[108:111], v[152:155], v[210:213], v[108:111]
	v_mfma_f32_16x16x32_bf16 v[92:95], v[146:149], v[214:217], v[92:95]
	v_mfma_f32_16x16x32_bf16 v[92:95], v[152:155], v[218:221], v[92:95]
	v_mfma_f32_16x16x32_bf16 v[76:79], v[146:149], v[222:225], v[76:79]
	v_mfma_f32_16x16x32_bf16 v[76:79], v[152:155], v[226:229], v[76:79]
	v_mfma_f32_16x16x32_bf16 v[68:71], v[172:175], v[222:225], v[68:71]
	v_mfma_f32_16x16x32_bf16 v[68:71], v[178:181], v[226:229], v[68:71]
	v_mfma_f32_16x16x32_bf16 v[84:87], v[172:175], v[214:217], v[84:87]
	v_mfma_f32_16x16x32_bf16 v[84:87], v[178:181], v[218:221], v[84:87]
	v_mfma_f32_16x16x32_bf16 v[100:103], v[172:175], v[206:209], v[100:103]
	v_mfma_f32_16x16x32_bf16 v[100:103], v[178:181], v[210:213], v[100:103]
	v_mfma_f32_16x16x32_bf16 v[116:119], v[172:175], v[198:201], v[116:119]
	v_mfma_f32_16x16x32_bf16 v[116:119], v[178:181], v[202:205], v[116:119]
	v_mfma_f32_16x16x32_bf16 v[120:123], v[182:185], v[198:201], v[120:123]
	v_mfma_f32_16x16x32_bf16 v[120:123], v[186:189], v[202:205], v[120:123]
	v_mfma_f32_16x16x32_bf16 v[104:107], v[182:185], v[206:209], v[104:107]
	v_mfma_f32_16x16x32_bf16 v[104:107], v[186:189], v[210:213], v[104:107]
	v_mfma_f32_16x16x32_bf16 v[88:91], v[182:185], v[214:217], v[88:91]
	v_mfma_f32_16x16x32_bf16 v[88:91], v[186:189], v[218:221], v[88:91]
	v_mfma_f32_16x16x32_bf16 v[72:75], v[182:185], v[222:225], v[72:75]
	v_mfma_f32_16x16x32_bf16 v[72:75], v[186:189], v[226:229], v[72:75]
	v_mfma_f32_16x16x32_bf16 v[64:67], v[190:193], v[222:225], v[64:67]
	v_mfma_f32_16x16x32_bf16 v[64:67], v[194:197], v[226:229], v[64:67]
	v_mfma_f32_16x16x32_bf16 v[80:83], v[190:193], v[214:217], v[80:83]
	v_mfma_f32_16x16x32_bf16 v[80:83], v[194:197], v[218:221], v[80:83]
	v_mfma_f32_16x16x32_bf16 v[96:99], v[190:193], v[206:209], v[96:99]
	v_mfma_f32_16x16x32_bf16 v[96:99], v[194:197], v[210:213], v[96:99]
	v_mfma_f32_16x16x32_bf16 v[112:115], v[190:193], v[198:201], v[112:115]
	v_mfma_f32_16x16x32_bf16 v[112:115], v[194:197], v[202:205], v[112:115]
	s_setprio 0
	s_barrier
	s_add_i32 s20, s33, s42
	v_lshl_add_u64 v[158:159], v[158:159], 0, s[8:9]
	s_mov_b32 m0, s20
	ds_read_b128 v[198:201], v171 offset:49152
	ds_read_b128 v[202:205], v171 offset:50176
	ds_read_b128 v[206:209], v171 offset:51200
	ds_read_b128 v[210:213], v171 offset:52224
	ds_read_b128 v[214:217], v171 offset:53248
	ds_read_b128 v[218:221], v171 offset:54272
	ds_read_b128 v[222:225], v171 offset:55296
	ds_read_b128 v[226:229], v171 offset:56320
	global_load_lds_dwordx4 v[158:159], off
	s_add_i32 m0, s20, 0x2000
	s_add_u32 s20, s38, 0x40080
	v_lshl_add_u64 v[158:159], v[164:165], 0, s[8:9]
	s_addc_u32 s21, s39, 0
	s_add_i32 s33, s62, s42
	global_load_lds_dwordx4 v[158:159], off
	v_lshl_add_u64 v[158:159], s[20:21], 0, v[132:133]
	s_mov_b32 m0, s33
	s_nop 0
	global_load_lds_dwordx4 v[158:159], off
	v_lshl_add_u64 v[158:159], s[20:21], 0, v[128:129]
	s_add_i32 m0, s33, 0x2000
	s_nop 0
	global_load_lds_dwordx4 v[158:159], off
	v_lshl_add_u64 v[158:159], v[168:169], 0, s[8:9]
	s_mov_b32 m0, s49
	s_nop 0
	global_load_lds_dwordx4 v[158:159], off
	v_lshl_add_u64 v[158:159], v[230:231], 0, s[8:9]
	s_mov_b32 m0, s50
	s_nop 0
	global_load_lds_dwordx4 v[158:159], off
	s_waitcnt vmcnt(8)
	s_waitcnt lgkmcnt(0)
	s_barrier
	s_setprio 1
	s_waitcnt lgkmcnt(0)
	v_mfma_f32_16x16x32_bf16 v[60:63], v[146:149], v[198:201], v[60:63]
	v_mfma_f32_16x16x32_bf16 v[60:63], v[152:155], v[202:205], v[60:63]
	v_mfma_f32_16x16x32_bf16 v[44:47], v[146:149], v[206:209], v[44:47]
	v_mfma_f32_16x16x32_bf16 v[44:47], v[152:155], v[210:213], v[44:47]
	v_mfma_f32_16x16x32_bf16 v[28:31], v[146:149], v[214:217], v[28:31]
	v_mfma_f32_16x16x32_bf16 v[28:31], v[152:155], v[218:221], v[28:31]
	v_mfma_f32_16x16x32_bf16 v[12:15], v[146:149], v[222:225], v[12:15]
	v_mfma_f32_16x16x32_bf16 v[12:15], v[152:155], v[226:229], v[12:15]
	v_mfma_f32_16x16x32_bf16 v[4:7], v[172:175], v[222:225], v[4:7]
	v_mfma_f32_16x16x32_bf16 v[4:7], v[178:181], v[226:229], v[4:7]
	v_mfma_f32_16x16x32_bf16 v[20:23], v[172:175], v[214:217], v[20:23]
	v_mfma_f32_16x16x32_bf16 v[20:23], v[178:181], v[218:221], v[20:23]
	v_mfma_f32_16x16x32_bf16 v[36:39], v[172:175], v[206:209], v[36:39]
	v_mfma_f32_16x16x32_bf16 v[36:39], v[178:181], v[210:213], v[36:39]
	v_mfma_f32_16x16x32_bf16 v[52:55], v[172:175], v[198:201], v[52:55]
	v_mfma_f32_16x16x32_bf16 v[52:55], v[178:181], v[202:205], v[52:55]
	v_mfma_f32_16x16x32_bf16 v[56:59], v[182:185], v[198:201], v[56:59]
	v_mfma_f32_16x16x32_bf16 v[56:59], v[186:189], v[202:205], v[56:59]
	v_mfma_f32_16x16x32_bf16 v[40:43], v[182:185], v[206:209], v[40:43]
	v_mfma_f32_16x16x32_bf16 v[40:43], v[186:189], v[210:213], v[40:43]
	v_mfma_f32_16x16x32_bf16 v[24:27], v[182:185], v[214:217], v[24:27]
	v_mfma_f32_16x16x32_bf16 v[24:27], v[186:189], v[218:221], v[24:27]
	v_mfma_f32_16x16x32_bf16 v[8:11], v[182:185], v[222:225], v[8:11]
	v_mfma_f32_16x16x32_bf16 v[8:11], v[186:189], v[226:229], v[8:11]
	v_mfma_f32_16x16x32_bf16 v[0:3], v[190:193], v[222:225], v[0:3]
	v_mfma_f32_16x16x32_bf16 v[0:3], v[194:197], v[226:229], v[0:3]
	v_mfma_f32_16x16x32_bf16 v[16:19], v[190:193], v[214:217], v[16:19]
	v_mfma_f32_16x16x32_bf16 v[16:19], v[194:197], v[218:221], v[16:19]
	v_mfma_f32_16x16x32_bf16 v[32:35], v[190:193], v[206:209], v[32:35]
	v_mfma_f32_16x16x32_bf16 v[32:35], v[194:197], v[210:213], v[32:35]
	v_mfma_f32_16x16x32_bf16 v[48:51], v[190:193], v[198:201], v[48:51]
	v_mfma_f32_16x16x32_bf16 v[48:51], v[194:197], v[202:205], v[48:51]
	s_setprio 0
	s_barrier
	s_add_i32 s61, s61, 2
	s_add_u32 s36, s36, 0x100
	s_addc_u32 s37, s37, 0
	s_add_u32 s59, s59, 0x100
	s_addc_u32 s60, s60, 0
	s_cmp_gt_u32 s61, 13
	s_cbranch_scc0 .LBB0_721
	s_and_b64 vcc, exec, s[10:11]
	s_cbranch_vccz .LBB0_724
	s_barrier

.LBB0_801:
	ds_read_b128 v[128:131], v197
	ds_read_b128 v[132:135], v197 offset:1024
	ds_read_b128 v[136:139], v197 offset:2048
	ds_read_b128 v[140:143], v197 offset:3072
	ds_read_b128 v[144:147], v198
	ds_read_b128 v[148:151], v198 offset:1024
	ds_read_b128 v[152:155], v198 offset:2048
	ds_read_b128 v[156:159], v198 offset:3072
	s_add_u32 s16, s14, 0x100
	s_addc_u32 s17, s15, 0
	s_cmp_eq_u32 s47, 40
	s_cselect_b32 s21, s5, s17
	s_cselect_b32 s20, s4, s16
	s_cselect_b32 s19, s13, s46
	s_cselect_b32 s18, s12, s45
	v_lshl_add_u64 v[192:193], s[14:15], 0, v[172:173]
	s_add_i32 m0, s23, 0xc000
	ds_read_b128 v[160:163], v199
	ds_read_b128 v[180:183], v199 offset:1024
	ds_read_b128 v[184:187], v199 offset:2048
	ds_read_b128 v[188:191], v199 offset:3072
	ds_read_b128 v[200:203], v199 offset:4096
	ds_read_b128 v[204:207], v199 offset:5120
	ds_read_b128 v[208:211], v199 offset:6144
	ds_read_b128 v[212:215], v199 offset:7168
	global_load_lds_dwordx4 v[192:193], off
	v_lshl_add_u64 v[192:193], s[14:15], 0, v[174:175]
	s_add_i32 m0, s23, 0xe000
	s_nop 0
	global_load_lds_dwordx4 v[192:193], off
	s_waitcnt vmcnt(8)
	s_waitcnt lgkmcnt(0)
	s_barrier
	s_setprio 1
	s_waitcnt lgkmcnt(0)
	v_mfma_f32_16x16x32_bf16 v[124:127], v[128:131], v[160:163], v[124:127]
	v_mfma_f32_16x16x32_bf16 v[124:127], v[132:135], v[180:183], v[124:127]
	v_mfma_f32_16x16x32_bf16 v[112:115], v[128:131], v[184:187], v[112:115]
	v_mfma_f32_16x16x32_bf16 v[112:115], v[132:135], v[188:191], v[112:115]
	v_mfma_f32_16x16x32_bf16 v[96:99], v[128:131], v[200:203], v[96:99]
	v_mfma_f32_16x16x32_bf16 v[96:99], v[132:135], v[204:207], v[96:99]
	v_mfma_f32_16x16x32_bf16 v[80:83], v[128:131], v[208:211], v[80:83]
	v_mfma_f32_16x16x32_bf16 v[80:83], v[132:135], v[212:215], v[80:83]
	v_mfma_f32_16x16x32_bf16 v[72:75], v[136:139], v[208:211], v[72:75]
	v_mfma_f32_16x16x32_bf16 v[72:75], v[140:143], v[212:215], v[72:75]
	v_mfma_f32_16x16x32_bf16 v[88:91], v[136:139], v[200:203], v[88:91]
	v_mfma_f32_16x16x32_bf16 v[88:91], v[140:143], v[204:207], v[88:91]
	v_mfma_f32_16x16x32_bf16 v[104:107], v[136:139], v[184:187], v[104:107]
	v_mfma_f32_16x16x32_bf16 v[104:107], v[140:143], v[188:191], v[104:107]
	v_mfma_f32_16x16x32_bf16 v[120:123], v[136:139], v[160:163], v[120:123]
	v_mfma_f32_16x16x32_bf16 v[120:123], v[140:143], v[180:183], v[120:123]
	v_mfma_f32_16x16x32_bf16 v[116:119], v[144:147], v[160:163], v[116:119]
	v_mfma_f32_16x16x32_bf16 v[116:119], v[148:151], v[180:183], v[116:119]
	v_mfma_f32_16x16x32_bf16 v[100:103], v[144:147], v[184:187], v[100:103]
	v_mfma_f32_16x16x32_bf16 v[100:103], v[148:151], v[188:191], v[100:103]
	v_mfma_f32_16x16x32_bf16 v[84:87], v[144:147], v[200:203], v[84:87]
	v_mfma_f32_16x16x32_bf16 v[84:87], v[148:151], v[204:207], v[84:87]
	v_mfma_f32_16x16x32_bf16 v[68:71], v[144:147], v[208:211], v[68:71]
	v_mfma_f32_16x16x32_bf16 v[68:71], v[148:151], v[212:215], v[68:71]
	v_mfma_f32_16x16x32_bf16 v[64:67], v[152:155], v[208:211], v[64:67]
	v_mfma_f32_16x16x32_bf16 v[64:67], v[156:159], v[212:215], v[64:67]
	v_mfma_f32_16x16x32_bf16 v[76:79], v[152:155], v[200:203], v[76:79]
	v_mfma_f32_16x16x32_bf16 v[76:79], v[156:159], v[204:207], v[76:79]
	v_mfma_f32_16x16x32_bf16 v[92:95], v[152:155], v[184:187], v[92:95]
	v_mfma_f32_16x16x32_bf16 v[92:95], v[156:159], v[188:191], v[92:95]
	v_mfma_f32_16x16x32_bf16 v[108:111], v[152:155], v[160:163], v[108:111]
	v_mfma_f32_16x16x32_bf16 v[108:111], v[156:159], v[180:183], v[108:111]
	s_setprio 0
	s_barrier
	s_add_i32 s14, s39, s22
	v_lshl_add_u64 v[192:193], s[18:19], 0, v[166:167]
	s_mov_b32 m0, s14
	ds_read_b128 v[160:163], v199 offset:16384
	ds_read_b128 v[180:183], v199 offset:17408
	ds_read_b128 v[184:187], v199 offset:18432
	ds_read_b128 v[188:191], v199 offset:19456
	ds_read_b128 v[200:203], v199 offset:20480
	ds_read_b128 v[204:207], v199 offset:21504
	ds_read_b128 v[208:211], v199 offset:22528
	ds_read_b128 v[212:215], v199 offset:23552
	global_load_lds_dwordx4 v[192:193], off
	s_add_i32 m0, s14, 0x2000
	s_add_u32 s14, s18, 0xb0000
	v_lshl_add_u64 v[216:217], s[18:19], 0, v[170:171]
	s_addc_u32 s15, s19, 0
	s_add_i32 s48, s40, s22
	global_load_lds_dwordx4 v[216:217], off
	v_lshl_add_u64 v[218:219], s[14:15], 0, v[166:167]
	s_mov_b32 m0, s48
	v_lshl_add_u64 v[220:221], s[20:21], 0, v[168:169]
	global_load_lds_dwordx4 v[218:219], off
	v_lshl_add_u64 v[218:219], s[14:15], 0, v[170:171]
	s_add_i32 m0, s48, 0x2000
	s_nop 0
	global_load_lds_dwordx4 v[218:219], off
	v_lshl_add_u64 v[218:219], s[20:21], 0, v[164:165]
	s_mov_b32 m0, s23
	s_nop 0
	global_load_lds_dwordx4 v[218:219], off
	s_mov_b32 m0, s30
	s_nop 0
	global_load_lds_dwordx4 v[220:221], off
	s_waitcnt vmcnt(8)
	s_waitcnt lgkmcnt(0)
	s_barrier
	s_setprio 1
	s_waitcnt lgkmcnt(0)
	v_mfma_f32_16x16x32_bf16 v[60:63], v[128:131], v[160:163], v[60:63]
	v_mfma_f32_16x16x32_bf16 v[60:63], v[132:135], v[180:183], v[60:63]
	v_mfma_f32_16x16x32_bf16 v[48:51], v[128:131], v[184:187], v[48:51]
	v_mfma_f32_16x16x32_bf16 v[48:51], v[132:135], v[188:191], v[48:51]
	v_mfma_f32_16x16x32_bf16 v[32:35], v[128:131], v[200:203], v[32:35]
	v_mfma_f32_16x16x32_bf16 v[32:35], v[132:135], v[204:207], v[32:35]
	v_mfma_f32_16x16x32_bf16 v[16:19], v[128:131], v[208:211], v[16:19]
	v_mfma_f32_16x16x32_bf16 v[16:19], v[132:135], v[212:215], v[16:19]
	v_mfma_f32_16x16x32_bf16 v[8:11], v[136:139], v[208:211], v[8:11]
	v_mfma_f32_16x16x32_bf16 v[8:11], v[140:143], v[212:215], v[8:11]
	v_mfma_f32_16x16x32_bf16 v[24:27], v[136:139], v[200:203], v[24:27]
	v_mfma_f32_16x16x32_bf16 v[24:27], v[140:143], v[204:207], v[24:27]
	v_mfma_f32_16x16x32_bf16 v[40:43], v[136:139], v[184:187], v[40:43]
	v_mfma_f32_16x16x32_bf16 v[40:43], v[140:143], v[188:191], v[40:43]
	v_mfma_f32_16x16x32_bf16 v[56:59], v[136:139], v[160:163], v[56:59]
	v_mfma_f32_16x16x32_bf16 v[56:59], v[140:143], v[180:183], v[56:59]
	v_mfma_f32_16x16x32_bf16 v[52:55], v[144:147], v[160:163], v[52:55]
	v_mfma_f32_16x16x32_bf16 v[52:55], v[148:151], v[180:183], v[52:55]
	v_mfma_f32_16x16x32_bf16 v[36:39], v[144:147], v[184:187], v[36:39]
	v_mfma_f32_16x16x32_bf16 v[36:39], v[148:151], v[188:191], v[36:39]
	v_mfma_f32_16x16x32_bf16 v[20:23], v[144:147], v[200:203], v[20:23]
	v_mfma_f32_16x16x32_bf16 v[20:23], v[148:151], v[204:207], v[20:23]
	v_mfma_f32_16x16x32_bf16 v[4:7], v[144:147], v[208:211], v[4:7]
	v_mfma_f32_16x16x32_bf16 v[4:7], v[148:151], v[212:215], v[4:7]
	v_mfma_f32_16x16x32_bf16 v[0:3], v[152:155], v[208:211], v[0:3]
	v_mfma_f32_16x16x32_bf16 v[0:3], v[156:159], v[212:215], v[0:3]
	v_mfma_f32_16x16x32_bf16 v[12:15], v[152:155], v[200:203], v[12:15]
	v_mfma_f32_16x16x32_bf16 v[12:15], v[156:159], v[204:207], v[12:15]
	v_mfma_f32_16x16x32_bf16 v[28:31], v[152:155], v[184:187], v[28:31]
	v_mfma_f32_16x16x32_bf16 v[28:31], v[156:159], v[188:191], v[28:31]
	v_mfma_f32_16x16x32_bf16 v[44:47], v[152:155], v[160:163], v[44:47]
	v_mfma_f32_16x16x32_bf16 v[44:47], v[156:159], v[180:183], v[44:47]
	s_setprio 0
	s_barrier
	s_add_i32 s48, 0, 0x18000
	s_add_i32 s49, 0, 0x1c000
	v_add_u32_e32 v140, s48, v195
	v_add_u32_e32 v156, s49, v195
	ds_read_b128 v[128:131], v140
	ds_read_b128 v[132:135], v140 offset:1024
	ds_read_b128 v[136:139], v140 offset:2048
	ds_read_b128 v[140:143], v140 offset:3072
	ds_read_b128 v[144:147], v156
	ds_read_b128 v[148:151], v156 offset:1024
	ds_read_b128 v[152:155], v156 offset:2048
	ds_read_b128 v[156:159], v156 offset:3072
	s_add_u32 s14, s20, 0xb0000
	s_addc_u32 s15, s21, 0
	s_mov_b32 m0, s31
	v_lshl_add_u64 v[222:223], s[14:15], 0, v[164:165]
	ds_read_b128 v[160:163], v199 offset:32768
	ds_read_b128 v[180:183], v199 offset:33792
	ds_read_b128 v[184:187], v199 offset:34816
	ds_read_b128 v[188:191], v199 offset:35840
	ds_read_b128 v[200:203], v199 offset:36864
	ds_read_b128 v[204:207], v199 offset:37888
	ds_read_b128 v[208:211], v199 offset:38912
	ds_read_b128 v[212:215], v199 offset:39936
	global_load_lds_dwordx4 v[222:223], off
	v_lshl_add_u64 v[222:223], s[14:15], 0, v[168:169]
	s_mov_b32 m0, s33
	s_nop 0
	global_load_lds_dwordx4 v[222:223], off
	s_waitcnt vmcnt(8)
	s_waitcnt lgkmcnt(0)
	s_barrier
	s_setprio 1
	s_waitcnt lgkmcnt(0)
	v_mfma_f32_16x16x32_bf16 v[124:127], v[128:131], v[160:163], v[124:127]
	v_mfma_f32_16x16x32_bf16 v[124:127], v[132:135], v[180:183], v[124:127]
	v_mfma_f32_16x16x32_bf16 v[112:115], v[128:131], v[184:187], v[112:115]
	v_mfma_f32_16x16x32_bf16 v[112:115], v[132:135], v[188:191], v[112:115]
	v_mfma_f32_16x16x32_bf16 v[96:99], v[128:131], v[200:203], v[96:99]
	v_mfma_f32_16x16x32_bf16 v[96:99], v[132:135], v[204:207], v[96:99]
	v_mfma_f32_16x16x32_bf16 v[80:83], v[128:131], v[208:211], v[80:83]
	v_mfma_f32_16x16x32_bf16 v[80:83], v[132:135], v[212:215], v[80:83]
	v_mfma_f32_16x16x32_bf16 v[72:75], v[136:139], v[208:211], v[72:75]
	v_mfma_f32_16x16x32_bf16 v[72:75], v[140:143], v[212:215], v[72:75]
	v_mfma_f32_16x16x32_bf16 v[88:91], v[136:139], v[200:203], v[88:91]
	v_mfma_f32_16x16x32_bf16 v[88:91], v[140:143], v[204:207], v[88:91]
	v_mfma_f32_16x16x32_bf16 v[104:107], v[136:139], v[184:187], v[104:107]
	v_mfma_f32_16x16x32_bf16 v[104:107], v[140:143], v[188:191], v[104:107]
	v_mfma_f32_16x16x32_bf16 v[120:123], v[136:139], v[160:163], v[120:123]
	v_mfma_f32_16x16x32_bf16 v[120:123], v[140:143], v[180:183], v[120:123]
	v_mfma_f32_16x16x32_bf16 v[116:119], v[144:147], v[160:163], v[116:119]
	v_mfma_f32_16x16x32_bf16 v[116:119], v[148:151], v[180:183], v[116:119]
	v_mfma_f32_16x16x32_bf16 v[100:103], v[144:147], v[184:187], v[100:103]
	v_mfma_f32_16x16x32_bf16 v[100:103], v[148:151], v[188:191], v[100:103]
	v_mfma_f32_16x16x32_bf16 v[84:87], v[144:147], v[200:203], v[84:87]
	v_mfma_f32_16x16x32_bf16 v[84:87], v[148:151], v[204:207], v[84:87]
	v_mfma_f32_16x16x32_bf16 v[68:71], v[144:147], v[208:211], v[68:71]
	v_mfma_f32_16x16x32_bf16 v[68:71], v[148:151], v[212:215], v[68:71]
	v_mfma_f32_16x16x32_bf16 v[64:67], v[152:155], v[208:211], v[64:67]
	v_mfma_f32_16x16x32_bf16 v[64:67], v[156:159], v[212:215], v[64:67]
	v_mfma_f32_16x16x32_bf16 v[76:79], v[152:155], v[200:203], v[76:79]
	v_mfma_f32_16x16x32_bf16 v[76:79], v[156:159], v[204:207], v[76:79]
	v_mfma_f32_16x16x32_bf16 v[92:95], v[152:155], v[184:187], v[92:95]
	v_mfma_f32_16x16x32_bf16 v[92:95], v[156:159], v[188:191], v[92:95]
	v_mfma_f32_16x16x32_bf16 v[108:111], v[152:155], v[160:163], v[108:111]
	v_mfma_f32_16x16x32_bf16 v[108:111], v[156:159], v[180:183], v[108:111]
	s_setprio 0
	s_barrier
	s_add_i32 s14, s48, s22
	v_lshl_add_u64 v[192:193], v[192:193], 0, s[8:9]
	s_mov_b32 m0, s14
	ds_read_b128 v[160:163], v199 offset:49152
	ds_read_b128 v[180:183], v199 offset:50176
	ds_read_b128 v[184:187], v199 offset:51200
	ds_read_b128 v[188:191], v199 offset:52224
	ds_read_b128 v[200:203], v199 offset:53248
	ds_read_b128 v[204:207], v199 offset:54272
	ds_read_b128 v[208:211], v199 offset:55296
	ds_read_b128 v[212:215], v199 offset:56320
	global_load_lds_dwordx4 v[192:193], off
	s_add_i32 m0, s14, 0x2000
	s_add_u32 s14, s18, 0xb0080
	v_lshl_add_u64 v[192:193], v[216:217], 0, s[8:9]
	s_addc_u32 s15, s19, 0
	s_add_i32 s18, s49, s22
	global_load_lds_dwordx4 v[192:193], off
	v_lshl_add_u64 v[192:193], s[14:15], 0, v[166:167]
	s_mov_b32 m0, s18
	s_nop 0
	global_load_lds_dwordx4 v[192:193], off
	v_lshl_add_u64 v[192:193], s[14:15], 0, v[170:171]
	s_add_i32 m0, s18, 0x2000
	s_nop 0
	global_load_lds_dwordx4 v[192:193], off
	v_lshl_add_u64 v[192:193], v[218:219], 0, s[8:9]
	s_mov_b32 m0, s36
	s_nop 0
	global_load_lds_dwordx4 v[192:193], off
	v_lshl_add_u64 v[192:193], v[220:221], 0, s[8:9]
	s_mov_b32 m0, s37
	s_nop 0
	global_load_lds_dwordx4 v[192:193], off
	s_waitcnt vmcnt(8)
	s_waitcnt lgkmcnt(0)
	s_barrier
	s_setprio 1
	s_waitcnt lgkmcnt(0)
	v_mfma_f32_16x16x32_bf16 v[60:63], v[128:131], v[160:163], v[60:63]
	v_mfma_f32_16x16x32_bf16 v[60:63], v[132:135], v[180:183], v[60:63]
	v_mfma_f32_16x16x32_bf16 v[48:51], v[128:131], v[184:187], v[48:51]
	v_mfma_f32_16x16x32_bf16 v[48:51], v[132:135], v[188:191], v[48:51]
	v_mfma_f32_16x16x32_bf16 v[32:35], v[128:131], v[200:203], v[32:35]
	v_mfma_f32_16x16x32_bf16 v[32:35], v[132:135], v[204:207], v[32:35]
	v_mfma_f32_16x16x32_bf16 v[16:19], v[128:131], v[208:211], v[16:19]
	v_mfma_f32_16x16x32_bf16 v[16:19], v[132:135], v[212:215], v[16:19]
	v_mfma_f32_16x16x32_bf16 v[8:11], v[136:139], v[208:211], v[8:11]
	v_mfma_f32_16x16x32_bf16 v[8:11], v[140:143], v[212:215], v[8:11]
	v_mfma_f32_16x16x32_bf16 v[24:27], v[136:139], v[200:203], v[24:27]
	v_mfma_f32_16x16x32_bf16 v[24:27], v[140:143], v[204:207], v[24:27]
	v_mfma_f32_16x16x32_bf16 v[40:43], v[136:139], v[184:187], v[40:43]
	v_mfma_f32_16x16x32_bf16 v[40:43], v[140:143], v[188:191], v[40:43]
	v_mfma_f32_16x16x32_bf16 v[56:59], v[136:139], v[160:163], v[56:59]
	v_mfma_f32_16x16x32_bf16 v[56:59], v[140:143], v[180:183], v[56:59]
	v_mfma_f32_16x16x32_bf16 v[52:55], v[144:147], v[160:163], v[52:55]
	v_mfma_f32_16x16x32_bf16 v[52:55], v[148:151], v[180:183], v[52:55]
	v_mfma_f32_16x16x32_bf16 v[36:39], v[144:147], v[184:187], v[36:39]
	v_mfma_f32_16x16x32_bf16 v[36:39], v[148:151], v[188:191], v[36:39]
	v_mfma_f32_16x16x32_bf16 v[20:23], v[144:147], v[200:203], v[20:23]
	v_mfma_f32_16x16x32_bf16 v[20:23], v[148:151], v[204:207], v[20:23]
	v_mfma_f32_16x16x32_bf16 v[4:7], v[144:147], v[208:211], v[4:7]
	v_mfma_f32_16x16x32_bf16 v[4:7], v[148:151], v[212:215], v[4:7]
	v_mfma_f32_16x16x32_bf16 v[0:3], v[152:155], v[208:211], v[0:3]
	v_mfma_f32_16x16x32_bf16 v[0:3], v[156:159], v[212:215], v[0:3]
	v_mfma_f32_16x16x32_bf16 v[12:15], v[152:155], v[200:203], v[12:15]
	v_mfma_f32_16x16x32_bf16 v[12:15], v[156:159], v[204:207], v[12:15]
	v_mfma_f32_16x16x32_bf16 v[28:31], v[152:155], v[184:187], v[28:31]
	v_mfma_f32_16x16x32_bf16 v[28:31], v[156:159], v[188:191], v[28:31]
	v_mfma_f32_16x16x32_bf16 v[44:47], v[152:155], v[160:163], v[44:47]
	v_mfma_f32_16x16x32_bf16 v[44:47], v[156:159], v[180:183], v[44:47]
	s_setprio 0
	s_barrier
	s_add_i32 s47, s47, 2
	s_add_u32 s45, s45, 0x100
	s_addc_u32 s46, s46, 0
	s_cmp_gt_u32 s47, 41
	s_mov_b64 s[14:15], s[16:17]
	s_cbranch_scc0 .LBB0_801
	s_and_b64 vcc, exec, s[10:11]
	s_cbranch_vccz .LBB0_804
	s_barrier
